# snake2 MFMA order: every adjacent MFMA either continues the same accumulator or shares a fragment register with its predecessor (k order of alternate pairs swapped), GEMM1/2/4
# baseline (speedup 1.0000x reference)
; #define PG8_STAGE(bufoff, gbase, voff) do { _Pragma("unroll") for (int _i = 0; _i < 2; ++_i) \
;         __builtin_amdgcn_global_load_lds((const unsigned*)((const char*)(gbase) + (voff)[_i]), (PG8_LAS unsigned*)(lds + (bufoff) + ldsw + _i * 8192), 16, 0, 0); } while (0)
; #define PG8_LDA(dst, b, h) do { _Pragma("unroll") for (int m = 0; m < 4; ++m) _Pragma("unroll") for (int k = 0; k < 2; ++k) dst[m][k] = *(const PG8_LAS bf16x8*)(lds + PG8_SA(b, h) + aoff + m * 2048 + k * 1024); } while (0)
; #define PG8_LDB(dst, b, h) do { _Pragma("unroll") for (int n = 0; n < 2; ++n) _Pragma("unroll") for (int k = 0; k < 2; ++k) dst[n][k] = *(const PG8_LAS bf16x8*)(lds + PG8_SB(b, h) + boff + n * 2048 + k * 1024); } while (0)
; #define PG8_MMA(ai, bj, At, Bt) do { __builtin_amdgcn_s_setprio(1); _Pragma("unroll") for (int m = 0; m < 4; ++m) _Pragma("unroll") for (int n = 0; n < 2; ++n) _Pragma("unroll") for (int k = 0; k < 2; ++k) \
;         acc[ai][bj][m][n] = __builtin_amdgcn_mfma_f32_16x16x32_bf16(Bt[n][k], At[m][k], acc[ai][bj][m][n], 0, 0, 0); __builtin_amdgcn_s_setprio(0); } while (0)
; #define PG8_WAIT_V(n) asm volatile("s_waitcnt vmcnt(" #n ")" ::: "memory")
; #define PG8_WAIT_L(n) asm volatile("s_waitcnt lgkmcnt(" #n ")" ::: "memory")
; #define PG8_BAR __builtin_amdgcn_s_barrier()
; #define PG8_SCHED __builtin_amdgcn_sched_barrier(0)
; template <class Epi, class Sched, bool ALIGN_EPI = false, bool SP2 = false>
; __device__ __forceinline__ void gemm_phase(PG8_LAS unsigned char* lds, const Gemm g, const Sched& S, const Epi& E) {
;     ...
;             if constexpr (SP2) {
;             PG8_LDB(B0, 0, 0); PG8_LDB(B1, 0, 1); PG8_SCHED; PG8_LDA(At, 0, 0); PG8_STAGE(PG8_SA(1, 1), a1 + hstep, voffA);
;             PG8_WAIT_V(8); PG8_WAIT_L(0); PG8_BAR; PG8_MMA(0, 0, At, B0); PG8_MMA(0, 1, At, B1); PG8_BAR; PG8_SCHED;
;             PG8_LDA(At, 0, 1); PG8_STAGE(PG8_SB(0, 0), b2, voffB); PG8_STAGE(PG8_SB(0, 1), b2 + hstep, voffB); PG8_STAGE(PG8_SA(0, 0), a2, voffA);
;             PG8_WAIT_V(8); PG8_WAIT_L(0); PG8_BAR; PG8_MMA(1, 0, At, B0); PG8_MMA(1, 1, At, B1); PG8_BAR; PG8_SCHED;
.LBB0_366:
	ds_read_b128 v[130:133], v228
	ds_read_b128 v[134:137], v228 offset:1024
	ds_read_b128 v[138:141], v228 offset:2048
	ds_read_b128 v[170:173], v228 offset:3072
	ds_read_b128 v[174:177], v229
	ds_read_b128 v[178:181], v229 offset:1024
	ds_read_b128 v[182:185], v229 offset:2048
	ds_read_b128 v[186:189], v229 offset:3072
	s_add_u32 s12, s10, 0xfff00080
	s_addc_u32 s13, s11, -1
	s_cmp_eq_u32 s80, 60
	s_cselect_b32 s15, s0, s13
	s_cselect_b32 s14, s1, s12
	s_cselect_b32 s13, s61, s77
	s_cselect_b32 s12, s69, s71
	s_add_i32 m0, s79, 0xc000
	ds_read_b128 v[190:193], v230
	ds_read_b128 v[194:197], v230 offset:1024
	ds_read_b128 v[198:201], v230 offset:2048
	ds_read_b128 v[202:205], v230 offset:3072
	ds_read_b128 v[206:209], v230 offset:4096
	ds_read_b128 v[210:213], v230 offset:5120
	ds_read_b128 v[214:217], v230 offset:6144
	ds_read_b128 v[218:221], v230 offset:7168
	global_load_lds_dwordx4 v164, s[10:11]
	s_add_i32 m0, s79, 0xe000
	s_nop 0
	global_load_lds_dwordx4 v166, s[10:11]
	s_waitcnt vmcnt(8)
	s_waitcnt lgkmcnt(0)
	s_barrier
	s_waitcnt lgkmcnt(0)
	v_mfma_f32_16x16x32_bf16 v[126:129], v[130:133], v[190:193], v[126:129]
	v_mfma_f32_16x16x32_bf16 v[126:129], v[134:137], v[194:197], v[126:129]
	v_mfma_f32_16x16x32_bf16 v[122:125], v[170:173], v[194:197], v[122:125]
	v_mfma_f32_16x16x32_bf16 v[122:125], v[138:141], v[190:193], v[122:125]
	v_mfma_f32_16x16x32_bf16 v[106:109], v[138:141], v[198:201], v[106:109]
	v_mfma_f32_16x16x32_bf16 v[106:109], v[170:173], v[202:205], v[106:109]
	v_mfma_f32_16x16x32_bf16 v[110:113], v[134:137], v[202:205], v[110:113]
	v_mfma_f32_16x16x32_bf16 v[110:113], v[130:133], v[198:201], v[110:113]
	v_mfma_f32_16x16x32_bf16 v[94:97], v[130:133], v[206:209], v[94:97]
	v_mfma_f32_16x16x32_bf16 v[94:97], v[134:137], v[210:213], v[94:97]
	v_mfma_f32_16x16x32_bf16 v[90:93], v[170:173], v[210:213], v[90:93]
	v_mfma_f32_16x16x32_bf16 v[90:93], v[138:141], v[206:209], v[90:93]
	v_mfma_f32_16x16x32_bf16 v[74:77], v[138:141], v[214:217], v[74:77]
	v_mfma_f32_16x16x32_bf16 v[74:77], v[170:173], v[218:221], v[74:77]
	v_mfma_f32_16x16x32_bf16 v[78:81], v[134:137], v[218:221], v[78:81]
	v_mfma_f32_16x16x32_bf16 v[78:81], v[130:133], v[214:217], v[78:81]
	v_mfma_f32_16x16x32_bf16 v[118:121], v[174:177], v[190:193], v[118:121]
	v_mfma_f32_16x16x32_bf16 v[118:121], v[178:181], v[194:197], v[118:121]
	v_mfma_f32_16x16x32_bf16 v[114:117], v[186:189], v[194:197], v[114:117]
	v_mfma_f32_16x16x32_bf16 v[114:117], v[182:185], v[190:193], v[114:117]
	v_mfma_f32_16x16x32_bf16 v[98:101], v[182:185], v[198:201], v[98:101]
	v_mfma_f32_16x16x32_bf16 v[98:101], v[186:189], v[202:205], v[98:101]
	v_mfma_f32_16x16x32_bf16 v[102:105], v[178:181], v[202:205], v[102:105]
	v_mfma_f32_16x16x32_bf16 v[102:105], v[174:177], v[198:201], v[102:105]
	v_mfma_f32_16x16x32_bf16 v[86:89], v[174:177], v[206:209], v[86:89]
	v_mfma_f32_16x16x32_bf16 v[86:89], v[178:181], v[210:213], v[86:89]
	v_mfma_f32_16x16x32_bf16 v[82:85], v[186:189], v[210:213], v[82:85]
	v_mfma_f32_16x16x32_bf16 v[82:85], v[182:185], v[206:209], v[82:85]
	v_mfma_f32_16x16x32_bf16 v[66:69], v[182:185], v[214:217], v[66:69]
	v_mfma_f32_16x16x32_bf16 v[66:69], v[186:189], v[218:221], v[66:69]
	v_mfma_f32_16x16x32_bf16 v[70:73], v[178:181], v[218:221], v[70:73]
	v_mfma_f32_16x16x32_bf16 v[70:73], v[174:177], v[214:217], v[70:73]
	s_barrier
	s_add_i32 s81, s63, s67
	s_mov_b32 m0, s81
	ds_read_b128 v[190:193], v230 offset:16384
	ds_read_b128 v[194:197], v230 offset:17408
	ds_read_b128 v[198:201], v230 offset:18432
	ds_read_b128 v[202:205], v230 offset:19456
	ds_read_b128 v[206:209], v230 offset:20480
	ds_read_b128 v[210:213], v230 offset:21504
	ds_read_b128 v[214:217], v230 offset:22528
	ds_read_b128 v[218:221], v230 offset:23552
	global_load_lds_dwordx4 v144, s[12:13]
	s_add_i32 m0, s81, 0x2000
	s_add_u32 s82, s12, 0x100000
	s_addc_u32 s83, s13, 0
	s_add_i32 s81, s94, s67
	global_load_lds_dwordx4 v148, s[12:13]
	s_mov_b32 m0, s81
	s_nop 0
	global_load_lds_dwordx4 v144, s[82:83]
	s_add_i32 m0, s81, 0x2000
	s_nop 0
	global_load_lds_dwordx4 v148, s[82:83]
	s_mov_b32 m0, s79
	s_nop 0
	global_load_lds_dwordx4 v142, s[14:15]
	s_mov_b32 m0, s88
	s_nop 0
	global_load_lds_dwordx4 v146, s[14:15]
	s_waitcnt vmcnt(8)
	s_waitcnt lgkmcnt(0)
	s_barrier
	s_waitcnt lgkmcnt(0)
	v_mfma_f32_16x16x32_bf16 v[62:65], v[130:133], v[190:193], v[62:65]
	v_mfma_f32_16x16x32_bf16 v[62:65], v[134:137], v[194:197], v[62:65]
	v_mfma_f32_16x16x32_bf16 v[58:61], v[170:173], v[194:197], v[58:61]
	v_mfma_f32_16x16x32_bf16 v[58:61], v[138:141], v[190:193], v[58:61]
	v_mfma_f32_16x16x32_bf16 v[42:45], v[138:141], v[198:201], v[42:45]
	v_mfma_f32_16x16x32_bf16 v[42:45], v[170:173], v[202:205], v[42:45]
	v_mfma_f32_16x16x32_bf16 v[46:49], v[134:137], v[202:205], v[46:49]
	v_mfma_f32_16x16x32_bf16 v[46:49], v[130:133], v[198:201], v[46:49]
	v_mfma_f32_16x16x32_bf16 v[30:33], v[130:133], v[206:209], v[30:33]
	v_mfma_f32_16x16x32_bf16 v[30:33], v[134:137], v[210:213], v[30:33]
	v_mfma_f32_16x16x32_bf16 v[26:29], v[170:173], v[210:213], v[26:29]
	v_mfma_f32_16x16x32_bf16 v[26:29], v[138:141], v[206:209], v[26:29]
	v_mfma_f32_16x16x32_bf16 v[10:13], v[138:141], v[214:217], v[10:13]
	v_mfma_f32_16x16x32_bf16 v[10:13], v[170:173], v[218:221], v[10:13]
	v_mfma_f32_16x16x32_bf16 v[14:17], v[134:137], v[218:221], v[14:17]
	v_mfma_f32_16x16x32_bf16 v[14:17], v[130:133], v[214:217], v[14:17]
	v_mfma_f32_16x16x32_bf16 v[54:57], v[174:177], v[190:193], v[54:57]
	v_mfma_f32_16x16x32_bf16 v[54:57], v[178:181], v[194:197], v[54:57]
	v_mfma_f32_16x16x32_bf16 v[50:53], v[186:189], v[194:197], v[50:53]
	v_mfma_f32_16x16x32_bf16 v[50:53], v[182:185], v[190:193], v[50:53]
	v_mfma_f32_16x16x32_bf16 v[34:37], v[182:185], v[198:201], v[34:37]
	v_mfma_f32_16x16x32_bf16 v[34:37], v[186:189], v[202:205], v[34:37]
	v_mfma_f32_16x16x32_bf16 v[38:41], v[178:181], v[202:205], v[38:41]
	v_mfma_f32_16x16x32_bf16 v[38:41], v[174:177], v[198:201], v[38:41]
	v_mfma_f32_16x16x32_bf16 v[22:25], v[174:177], v[206:209], v[22:25]
	v_mfma_f32_16x16x32_bf16 v[22:25], v[178:181], v[210:213], v[22:25]
	v_mfma_f32_16x16x32_bf16 v[18:21], v[186:189], v[210:213], v[18:21]
	v_mfma_f32_16x16x32_bf16 v[18:21], v[182:185], v[206:209], v[18:21]
	v_mfma_f32_16x16x32_bf16 v[2:5], v[182:185], v[214:217], v[2:5]
	v_mfma_f32_16x16x32_bf16 v[2:5], v[186:189], v[218:221], v[2:5]
	v_mfma_f32_16x16x32_bf16 v[6:9], v[178:181], v[218:221], v[6:9]
	v_mfma_f32_16x16x32_bf16 v[6:9], v[174:177], v[214:217], v[6:9]
	s_barrier
; #define PG8_STAGE(bufoff, gbase, voff) do { _Pragma("unroll") for (int _i = 0; _i < 2; ++_i) \
;         __builtin_amdgcn_global_load_lds((const unsigned*)((const char*)(gbase) + (voff)[_i]), (PG8_LAS unsigned*)(lds + (bufoff) + ldsw + _i * 8192), 16, 0, 0); } while (0)
; #define PG8_LDA(dst, b, h) do { _Pragma("unroll") for (int m = 0; m < 4; ++m) _Pragma("unroll") for (int k = 0; k < 2; ++k) dst[m][k] = *(const PG8_LAS bf16x8*)(lds + PG8_SA(b, h) + aoff + m * 2048 + k * 1024); } while (0)
; #define PG8_LDB(dst, b, h) do { _Pragma("unroll") for (int n = 0; n < 2; ++n) _Pragma("unroll") for (int k = 0; k < 2; ++k) dst[n][k] = *(const PG8_LAS bf16x8*)(lds + PG8_SB(b, h) + boff + n * 2048 + k * 1024); } while (0)
; #define PG8_MMA(ai, bj, At, Bt) do { __builtin_amdgcn_s_setprio(1); _Pragma("unroll") for (int m = 0; m < 4; ++m) _Pragma("unroll") for (int n = 0; n < 2; ++n) _Pragma("unroll") for (int k = 0; k < 2; ++k) \
;         acc[ai][bj][m][n] = __builtin_amdgcn_mfma_f32_16x16x32_bf16(Bt[n][k], At[m][k], acc[ai][bj][m][n], 0, 0, 0); __builtin_amdgcn_s_setprio(0); } while (0)
; #define PG8_WAIT_V(n) asm volatile("s_waitcnt vmcnt(" #n ")" ::: "memory")
; template <class Epi, class Sched, bool ALIGN_EPI = false, bool SP2 = false>
; __device__ __forceinline__ void gemm_phase(PG8_LAS unsigned char* lds, const Gemm g, const Sched& S, const Epi& E) {
;     ...
;         for (int t = 0; t < ntc; t += 2) {
;             if constexpr (Epi::MID) { if (ntc == nt && t == (nt >> 1)) E.mid(acc, cur, wr, wc, fr, fq); }
;             const bool last = (t == ntc - 2);
;             const char* a1 = cA + (size_t)(t + 1) * kstep;
;             const char* a2 = last ? nA : cA + (size_t)(t + 2) * kstep; const char* b2 = last ? nB : cB + (size_t)(t + 2) * kstep;
;             const char* a3 = a2 + kstep; const char* b3 = b2 + kstep;
;             if (last && has_next) S.a_ready(nxt);
;     ...
;             PG8_LDB(B0, 1, 0); PG8_LDB(B1, 1, 1); PG8_SCHED; PG8_LDA(At, 1, 0); PG8_STAGE(PG8_SA(0, 1), a2 + hstep, voffA);
;             PG8_WAIT_V(8); PG8_WAIT_L(0); PG8_BAR; PG8_MMA(0, 0, At, B0); PG8_MMA(0, 1, At, B1); PG8_BAR; PG8_SCHED;
;             PG8_LDA(At, 1, 1); PG8_STAGE(PG8_SB(1, 0), b3, voffB); PG8_STAGE(PG8_SB(1, 1), b3 + hstep, voffB); PG8_STAGE(PG8_SA(1, 0), a3, voffA);
;             PG8_WAIT_V(8); PG8_WAIT_L(0); PG8_BAR; PG8_MMA(1, 0, At, B0); PG8_MMA(1, 1, At, B1); PG8_BAR; PG8_SCHED;
	s_add_i32 s81, 0, 0x18000
	v_add_u32_e32 v150, s81, v153
	s_add_i32 s82, 0, 0x1c000
	ds_read_b128 v[130:133], v150
	ds_read_b128 v[134:137], v150 offset:1024
	ds_read_b128 v[138:141], v150 offset:2048
	ds_read_b128 v[170:173], v150 offset:3072
	v_add_u32_e32 v150, s82, v153
	ds_read_b128 v[174:177], v150
	ds_read_b128 v[178:181], v150 offset:1024
	ds_read_b128 v[182:185], v150 offset:2048
	ds_read_b128 v[186:189], v150 offset:3072
	s_add_u32 s14, s14, 0x100000
	s_addc_u32 s15, s15, 0
	s_mov_b32 m0, s89
	ds_read_b128 v[190:193], v230 offset:32768
	ds_read_b128 v[194:197], v230 offset:33792
	ds_read_b128 v[198:201], v230 offset:34816
	ds_read_b128 v[202:205], v230 offset:35840
	ds_read_b128 v[206:209], v230 offset:36864
	ds_read_b128 v[210:213], v230 offset:37888
	ds_read_b128 v[214:217], v230 offset:38912
	ds_read_b128 v[218:221], v230 offset:39936
	global_load_lds_dwordx4 v142, s[14:15]
	s_mov_b32 m0, s90
	s_nop 0
	global_load_lds_dwordx4 v146, s[14:15]
	s_waitcnt vmcnt(8)
	s_waitcnt lgkmcnt(0)
	s_barrier
	s_waitcnt lgkmcnt(0)
	v_mfma_f32_16x16x32_bf16 v[126:129], v[130:133], v[190:193], v[126:129]
	v_mfma_f32_16x16x32_bf16 v[126:129], v[134:137], v[194:197], v[126:129]
	v_mfma_f32_16x16x32_bf16 v[122:125], v[170:173], v[194:197], v[122:125]
	v_mfma_f32_16x16x32_bf16 v[122:125], v[138:141], v[190:193], v[122:125]
	v_mfma_f32_16x16x32_bf16 v[106:109], v[138:141], v[198:201], v[106:109]
	v_mfma_f32_16x16x32_bf16 v[106:109], v[170:173], v[202:205], v[106:109]
	v_mfma_f32_16x16x32_bf16 v[110:113], v[134:137], v[202:205], v[110:113]
	v_mfma_f32_16x16x32_bf16 v[110:113], v[130:133], v[198:201], v[110:113]
	v_mfma_f32_16x16x32_bf16 v[94:97], v[130:133], v[206:209], v[94:97]
	v_mfma_f32_16x16x32_bf16 v[94:97], v[134:137], v[210:213], v[94:97]
	v_mfma_f32_16x16x32_bf16 v[90:93], v[170:173], v[210:213], v[90:93]
	v_mfma_f32_16x16x32_bf16 v[90:93], v[138:141], v[206:209], v[90:93]
	v_mfma_f32_16x16x32_bf16 v[74:77], v[138:141], v[214:217], v[74:77]
	v_mfma_f32_16x16x32_bf16 v[74:77], v[170:173], v[218:221], v[74:77]
	v_mfma_f32_16x16x32_bf16 v[78:81], v[134:137], v[218:221], v[78:81]
	v_mfma_f32_16x16x32_bf16 v[78:81], v[130:133], v[214:217], v[78:81]
	v_mfma_f32_16x16x32_bf16 v[118:121], v[174:177], v[190:193], v[118:121]
	v_mfma_f32_16x16x32_bf16 v[118:121], v[178:181], v[194:197], v[118:121]
	v_mfma_f32_16x16x32_bf16 v[114:117], v[186:189], v[194:197], v[114:117]
	v_mfma_f32_16x16x32_bf16 v[114:117], v[182:185], v[190:193], v[114:117]
	v_mfma_f32_16x16x32_bf16 v[98:101], v[182:185], v[198:201], v[98:101]
	v_mfma_f32_16x16x32_bf16 v[98:101], v[186:189], v[202:205], v[98:101]
	v_mfma_f32_16x16x32_bf16 v[102:105], v[178:181], v[202:205], v[102:105]
	v_mfma_f32_16x16x32_bf16 v[102:105], v[174:177], v[198:201], v[102:105]
	v_mfma_f32_16x16x32_bf16 v[86:89], v[174:177], v[206:209], v[86:89]
	v_mfma_f32_16x16x32_bf16 v[86:89], v[178:181], v[210:213], v[86:89]
	v_mfma_f32_16x16x32_bf16 v[82:85], v[186:189], v[210:213], v[82:85]
	v_mfma_f32_16x16x32_bf16 v[82:85], v[182:185], v[206:209], v[82:85]
	v_mfma_f32_16x16x32_bf16 v[66:69], v[182:185], v[214:217], v[66:69]
	v_mfma_f32_16x16x32_bf16 v[66:69], v[186:189], v[218:221], v[66:69]
	v_mfma_f32_16x16x32_bf16 v[70:73], v[178:181], v[218:221], v[70:73]
	v_mfma_f32_16x16x32_bf16 v[70:73], v[174:177], v[214:217], v[70:73]
	s_barrier
	s_add_u32 s100, s14, 0xfff00080
	s_addc_u32 s101, s15, -1
	s_add_u32 s98, s12, 0x80
	s_addc_u32 s99, s13, 0
	s_add_i32 s14, s81, s67
	s_mov_b32 m0, s14
	ds_read_b128 v[190:193], v230 offset:49152
	ds_read_b128 v[194:197], v230 offset:50176
	ds_read_b128 v[198:201], v230 offset:51200
	ds_read_b128 v[202:205], v230 offset:52224
	ds_read_b128 v[206:209], v230 offset:53248
	ds_read_b128 v[210:213], v230 offset:54272
	ds_read_b128 v[214:217], v230 offset:55296
	ds_read_b128 v[218:221], v230 offset:56320
	global_load_lds_dwordx4 v144, s[98:99]
	s_add_i32 m0, s14, 0x2000
	s_add_u32 s12, s12, 0x100080
	s_addc_u32 s13, s13, 0
	s_add_i32 s14, s82, s67
	global_load_lds_dwordx4 v148, s[98:99]
	s_mov_b32 m0, s14
	s_nop 0
	global_load_lds_dwordx4 v144, s[12:13]
	s_add_i32 m0, s14, 0x2000
	s_nop 0
	global_load_lds_dwordx4 v148, s[12:13]
	s_mov_b32 m0, s93
	s_nop 0
	global_load_lds_dwordx4 v142, s[100:101]
	s_mov_b32 m0, s62
	s_nop 0
	global_load_lds_dwordx4 v146, s[100:101]
	s_waitcnt vmcnt(8)
	s_waitcnt lgkmcnt(0)
	s_barrier
	s_waitcnt lgkmcnt(0)
	v_mfma_f32_16x16x32_bf16 v[62:65], v[130:133], v[190:193], v[62:65]
	v_mfma_f32_16x16x32_bf16 v[62:65], v[134:137], v[194:197], v[62:65]
	v_mfma_f32_16x16x32_bf16 v[58:61], v[170:173], v[194:197], v[58:61]
	v_mfma_f32_16x16x32_bf16 v[58:61], v[138:141], v[190:193], v[58:61]
	v_mfma_f32_16x16x32_bf16 v[42:45], v[138:141], v[198:201], v[42:45]
	v_mfma_f32_16x16x32_bf16 v[42:45], v[170:173], v[202:205], v[42:45]
	v_mfma_f32_16x16x32_bf16 v[46:49], v[134:137], v[202:205], v[46:49]
	v_mfma_f32_16x16x32_bf16 v[46:49], v[130:133], v[198:201], v[46:49]
	v_mfma_f32_16x16x32_bf16 v[30:33], v[130:133], v[206:209], v[30:33]
	v_mfma_f32_16x16x32_bf16 v[30:33], v[134:137], v[210:213], v[30:33]
	v_mfma_f32_16x16x32_bf16 v[26:29], v[170:173], v[210:213], v[26:29]
	v_mfma_f32_16x16x32_bf16 v[26:29], v[138:141], v[206:209], v[26:29]
	v_mfma_f32_16x16x32_bf16 v[10:13], v[138:141], v[214:217], v[10:13]
	v_mfma_f32_16x16x32_bf16 v[10:13], v[170:173], v[218:221], v[10:13]
	v_mfma_f32_16x16x32_bf16 v[14:17], v[134:137], v[218:221], v[14:17]
	v_mfma_f32_16x16x32_bf16 v[14:17], v[130:133], v[214:217], v[14:17]
	v_mfma_f32_16x16x32_bf16 v[54:57], v[174:177], v[190:193], v[54:57]
	v_mfma_f32_16x16x32_bf16 v[54:57], v[178:181], v[194:197], v[54:57]
	v_mfma_f32_16x16x32_bf16 v[50:53], v[186:189], v[194:197], v[50:53]
	v_mfma_f32_16x16x32_bf16 v[50:53], v[182:185], v[190:193], v[50:53]
	v_mfma_f32_16x16x32_bf16 v[34:37], v[182:185], v[198:201], v[34:37]
	v_mfma_f32_16x16x32_bf16 v[34:37], v[186:189], v[202:205], v[34:37]
	v_mfma_f32_16x16x32_bf16 v[38:41], v[178:181], v[202:205], v[38:41]
	v_mfma_f32_16x16x32_bf16 v[38:41], v[174:177], v[198:201], v[38:41]
	v_mfma_f32_16x16x32_bf16 v[22:25], v[174:177], v[206:209], v[22:25]
	v_mfma_f32_16x16x32_bf16 v[22:25], v[178:181], v[210:213], v[22:25]
	v_mfma_f32_16x16x32_bf16 v[18:21], v[186:189], v[210:213], v[18:21]
	v_mfma_f32_16x16x32_bf16 v[18:21], v[182:185], v[206:209], v[18:21]
	v_mfma_f32_16x16x32_bf16 v[2:5], v[182:185], v[214:217], v[2:5]
	v_mfma_f32_16x16x32_bf16 v[2:5], v[186:189], v[218:221], v[2:5]
	v_mfma_f32_16x16x32_bf16 v[6:9], v[178:181], v[218:221], v[6:9]
	v_mfma_f32_16x16x32_bf16 v[6:9], v[174:177], v[214:217], v[6:9]
	s_barrier
	s_add_i32 s80, s80, 2
	s_add_u32 s10, s10, 0x100
	s_addc_u32 s11, s11, 0
	s_add_u32 s71, s71, 0x100
	s_addc_u32 s77, s77, 0
	s_cmp_gt_u32 s80, 61
	s_cbranch_scc0 .LBB0_366
	s_and_b64 vcc, exec, s[28:29]
	s_cbranch_vccz .LBB0_369
	s_barrier

; #define PG8_STAGE(bufoff, gbase, voff) do { _Pragma("unroll") for (int _i = 0; _i < 2; ++_i) \
;         __builtin_amdgcn_global_load_lds((const unsigned*)((const char*)(gbase) + (voff)[_i]), (PG8_LAS unsigned*)(lds + (bufoff) + ldsw + _i * 8192), 16, 0, 0); } while (0)
; #define PG8_LDA(dst, b, h) do { _Pragma("unroll") for (int m = 0; m < 4; ++m) _Pragma("unroll") for (int k = 0; k < 2; ++k) dst[m][k] = *(const PG8_LAS bf16x8*)(lds + PG8_SA(b, h) + aoff + m * 2048 + k * 1024); } while (0)
; #define PG8_LDB(dst, b, h) do { _Pragma("unroll") for (int n = 0; n < 2; ++n) _Pragma("unroll") for (int k = 0; k < 2; ++k) dst[n][k] = *(const PG8_LAS bf16x8*)(lds + PG8_SB(b, h) + boff + n * 2048 + k * 1024); } while (0)
; #define PG8_MMA(ai, bj, At, Bt) do { __builtin_amdgcn_s_setprio(1); _Pragma("unroll") for (int m = 0; m < 4; ++m) _Pragma("unroll") for (int n = 0; n < 2; ++n) _Pragma("unroll") for (int k = 0; k < 2; ++k) \
;         acc[ai][bj][m][n] = __builtin_amdgcn_mfma_f32_16x16x32_bf16(Bt[n][k], At[m][k], acc[ai][bj][m][n], 0, 0, 0); __builtin_amdgcn_s_setprio(0); } while (0)
; #define PG8_WAIT_V(n) asm volatile("s_waitcnt vmcnt(" #n ")" ::: "memory")
; #define PG8_WAIT_L(n) asm volatile("s_waitcnt lgkmcnt(" #n ")" ::: "memory")
; #define PG8_BAR __builtin_amdgcn_s_barrier()
; #define PG8_SCHED __builtin_amdgcn_sched_barrier(0)
; template <class Epi, class Sched, bool ALIGN_EPI = false, bool SP2 = false>
; __device__ __forceinline__ void gemm_phase(PG8_LAS unsigned char* lds, const Gemm g, const Sched& S, const Epi& E) {
;     ...
;             if constexpr (SP2) {
;             PG8_LDB(B0, 0, 0); PG8_LDB(B1, 0, 1); PG8_SCHED; PG8_LDA(At, 0, 0); PG8_STAGE(PG8_SA(1, 1), a1 + hstep, voffA);
;             PG8_WAIT_V(8); PG8_WAIT_L(0); PG8_BAR; PG8_MMA(0, 0, At, B0); PG8_MMA(0, 1, At, B1); PG8_BAR; PG8_SCHED;
;             PG8_LDA(At, 0, 1); PG8_STAGE(PG8_SB(0, 0), b2, voffB); PG8_STAGE(PG8_SB(0, 1), b2 + hstep, voffB); PG8_STAGE(PG8_SA(0, 0), a2, voffA);
.LBB0_2487:
	v_add_u32_e32 v3, s67, v183
	s_add_i32 s81, s50, 2
	ds_read_b128 v[154:157], v3
	ds_read_b128 v[158:161], v3 offset:1024
	ds_read_b128 v[162:165], v3 offset:2048
	ds_read_b128 v[166:169], v3 offset:3072
	v_add_u32_e32 v3, s68, v183
	s_add_u32 s51, s42, s46
	ds_read_b128 v[170:173], v3
	ds_read_b128 v[174:177], v3 offset:1024
	ds_read_b128 v[178:181], v3 offset:2048
	ds_read_b128 v[184:187], v3 offset:3072
	s_addc_u32 s52, s43, s47
	s_add_u32 s51, s51, 0x100
	s_addc_u32 s52, s52, 0
	s_add_u32 s82, s79, s46
	s_addc_u32 s83, s80, s47
	s_cmp_eq_u32 s9, s50
	s_cselect_b32 s53, s27, s52
	s_cselect_b32 s52, s35, s51
	s_cselect_b32 s51, s31, s83
	s_cselect_b32 s50, s78, s82
	v_lshl_add_u64 v[4:5], v[150:151], 0, s[46:47]
	s_add_i32 m0, s11, 0xc000
	ds_read_b128 v[188:191], v211
	ds_read_b128 v[192:195], v211 offset:1024
	ds_read_b128 v[196:199], v211 offset:2048
	ds_read_b128 v[200:203], v211 offset:3072
	ds_read_b128 v[204:207], v211 offset:4096
	ds_read_b128 v[212:215], v211 offset:5120
	ds_read_b128 v[216:219], v211 offset:6144
	ds_read_b128 v[220:223], v211 offset:7168
	global_load_lds_dwordx4 v[4:5], off
	v_lshl_add_u64 v[4:5], v[152:153], 0, s[46:47]
	s_add_i32 m0, s11, 0xe000
	s_nop 0
	global_load_lds_dwordx4 v[4:5], off
	s_waitcnt vmcnt(8)
	s_waitcnt lgkmcnt(0)
	s_barrier
	s_waitcnt lgkmcnt(0)
	v_mfma_f32_16x16x32_bf16 v[130:133], v[154:157], v[188:191], v[130:133]
	v_mfma_f32_16x16x32_bf16 v[130:133], v[158:161], v[192:195], v[130:133]
	v_mfma_f32_16x16x32_bf16 v[126:129], v[166:169], v[192:195], v[126:129]
	v_mfma_f32_16x16x32_bf16 v[126:129], v[162:165], v[188:191], v[126:129]
	v_mfma_f32_16x16x32_bf16 v[110:113], v[162:165], v[196:199], v[110:113]
	v_mfma_f32_16x16x32_bf16 v[110:113], v[166:169], v[200:203], v[110:113]
	v_mfma_f32_16x16x32_bf16 v[114:117], v[158:161], v[200:203], v[114:117]
	v_mfma_f32_16x16x32_bf16 v[114:117], v[154:157], v[196:199], v[114:117]
	v_mfma_f32_16x16x32_bf16 v[98:101], v[154:157], v[204:207], v[98:101]
	v_mfma_f32_16x16x32_bf16 v[98:101], v[158:161], v[212:215], v[98:101]
	v_mfma_f32_16x16x32_bf16 v[94:97], v[166:169], v[212:215], v[94:97]
	v_mfma_f32_16x16x32_bf16 v[94:97], v[162:165], v[204:207], v[94:97]
	v_mfma_f32_16x16x32_bf16 v[78:81], v[162:165], v[216:219], v[78:81]
	v_mfma_f32_16x16x32_bf16 v[78:81], v[166:169], v[220:223], v[78:81]
	v_mfma_f32_16x16x32_bf16 v[82:85], v[158:161], v[220:223], v[82:85]
	v_mfma_f32_16x16x32_bf16 v[82:85], v[154:157], v[216:219], v[82:85]
	v_mfma_f32_16x16x32_bf16 v[122:125], v[170:173], v[188:191], v[122:125]
	v_mfma_f32_16x16x32_bf16 v[122:125], v[174:177], v[192:195], v[122:125]
	v_mfma_f32_16x16x32_bf16 v[118:121], v[184:187], v[192:195], v[118:121]
	v_mfma_f32_16x16x32_bf16 v[118:121], v[178:181], v[188:191], v[118:121]
	v_mfma_f32_16x16x32_bf16 v[102:105], v[178:181], v[196:199], v[102:105]
	v_mfma_f32_16x16x32_bf16 v[102:105], v[184:187], v[200:203], v[102:105]
	v_mfma_f32_16x16x32_bf16 v[106:109], v[174:177], v[200:203], v[106:109]
	v_mfma_f32_16x16x32_bf16 v[106:109], v[170:173], v[196:199], v[106:109]
	v_mfma_f32_16x16x32_bf16 v[90:93], v[170:173], v[204:207], v[90:93]
	v_mfma_f32_16x16x32_bf16 v[90:93], v[174:177], v[212:215], v[90:93]
	v_mfma_f32_16x16x32_bf16 v[86:89], v[184:187], v[212:215], v[86:89]
	v_mfma_f32_16x16x32_bf16 v[86:89], v[178:181], v[204:207], v[86:89]
	v_mfma_f32_16x16x32_bf16 v[70:73], v[178:181], v[216:219], v[70:73]
	v_mfma_f32_16x16x32_bf16 v[70:73], v[184:187], v[220:223], v[70:73]
	v_mfma_f32_16x16x32_bf16 v[74:77], v[174:177], v[220:223], v[74:77]
	v_mfma_f32_16x16x32_bf16 v[74:77], v[170:173], v[216:219], v[74:77]
	s_barrier
	s_add_i32 s82, s67, s55
	s_mov_b32 m0, s82
	ds_read_b128 v[188:191], v211 offset:16384
	ds_read_b128 v[192:195], v211 offset:17408
	ds_read_b128 v[196:199], v211 offset:18432
	ds_read_b128 v[200:203], v211 offset:19456
	ds_read_b128 v[204:207], v211 offset:20480
	ds_read_b128 v[212:215], v211 offset:21504
	ds_read_b128 v[216:219], v211 offset:22528
	ds_read_b128 v[220:223], v211 offset:23552
	global_load_lds_dwordx4 v134, s[50:51]
	s_add_i32 m0, s82, 0x2000
	s_add_u32 s82, s50, 0x100000
	s_addc_u32 s83, s51, 0
	s_add_i32 s84, s68, s55
	global_load_lds_dwordx4 v136, s[50:51]
	s_mov_b32 m0, s84
	s_nop 0
	global_load_lds_dwordx4 v134, s[82:83]
	s_add_i32 m0, s84, 0x2000
	s_nop 0
	global_load_lds_dwordx4 v136, s[82:83]
	s_mov_b32 m0, s11
	s_nop 0
	global_load_lds_dwordx4 v134, s[52:53]
	s_mov_b32 m0, s57
	s_nop 0
	global_load_lds_dwordx4 v136, s[52:53]
	s_waitcnt vmcnt(8)
	s_waitcnt lgkmcnt(0)
	s_barrier
; #define PG8_STAGE(bufoff, gbase, voff) do { _Pragma("unroll") for (int _i = 0; _i < 2; ++_i) \
;         __builtin_amdgcn_global_load_lds((const unsigned*)((const char*)(gbase) + (voff)[_i]), (PG8_LAS unsigned*)(lds + (bufoff) + ldsw + _i * 8192), 16, 0, 0); } while (0)
; #define PG8_LDA(dst, b, h) do { _Pragma("unroll") for (int m = 0; m < 4; ++m) _Pragma("unroll") for (int k = 0; k < 2; ++k) dst[m][k] = *(const PG8_LAS bf16x8*)(lds + PG8_SA(b, h) + aoff + m * 2048 + k * 1024); } while (0)
; #define PG8_LDB(dst, b, h) do { _Pragma("unroll") for (int n = 0; n < 2; ++n) _Pragma("unroll") for (int k = 0; k < 2; ++k) dst[n][k] = *(const PG8_LAS bf16x8*)(lds + PG8_SB(b, h) + boff + n * 2048 + k * 1024); } while (0)
; #define PG8_MMA(ai, bj, At, Bt) do { __builtin_amdgcn_s_setprio(1); _Pragma("unroll") for (int m = 0; m < 4; ++m) _Pragma("unroll") for (int n = 0; n < 2; ++n) _Pragma("unroll") for (int k = 0; k < 2; ++k) \
;         acc[ai][bj][m][n] = __builtin_amdgcn_mfma_f32_16x16x32_bf16(Bt[n][k], At[m][k], acc[ai][bj][m][n], 0, 0, 0); __builtin_amdgcn_s_setprio(0); } while (0)
; #define PG8_WAIT_V(n) asm volatile("s_waitcnt vmcnt(" #n ")" ::: "memory")
; #define PG8_WAIT_L(n) asm volatile("s_waitcnt lgkmcnt(" #n ")" ::: "memory")
; #define PG8_BAR __builtin_amdgcn_s_barrier()
; #define PG8_SCHED __builtin_amdgcn_sched_barrier(0)
; template <class Epi, class Sched, bool ALIGN_EPI = false, bool SP2 = false>
; __device__ __forceinline__ void gemm_phase(PG8_LAS unsigned char* lds, const Gemm g, const Sched& S, const Epi& E) {
;     ...
;             PG8_WAIT_V(8); PG8_WAIT_L(0); PG8_BAR; PG8_MMA(1, 0, At, B0); PG8_MMA(1, 1, At, B1); PG8_BAR; PG8_SCHED;
;             PG8_LDB(B0, 1, 0); PG8_LDB(B1, 1, 1); PG8_SCHED; PG8_LDA(At, 1, 0); PG8_STAGE(PG8_SA(0, 1), a2 + hstep, voffA);
;             PG8_WAIT_V(8); PG8_WAIT_L(0); PG8_BAR; PG8_MMA(0, 0, At, B0); PG8_MMA(0, 1, At, B1); PG8_BAR; PG8_SCHED;
	s_waitcnt lgkmcnt(0)
	v_mfma_f32_16x16x32_bf16 v[66:69], v[154:157], v[188:191], v[66:69]
	v_mfma_f32_16x16x32_bf16 v[66:69], v[158:161], v[192:195], v[66:69]
	v_mfma_f32_16x16x32_bf16 v[62:65], v[166:169], v[192:195], v[62:65]
	v_mfma_f32_16x16x32_bf16 v[62:65], v[162:165], v[188:191], v[62:65]
	v_mfma_f32_16x16x32_bf16 v[46:49], v[162:165], v[196:199], v[46:49]
	v_mfma_f32_16x16x32_bf16 v[46:49], v[166:169], v[200:203], v[46:49]
	v_mfma_f32_16x16x32_bf16 v[50:53], v[158:161], v[200:203], v[50:53]
	v_mfma_f32_16x16x32_bf16 v[50:53], v[154:157], v[196:199], v[50:53]
	v_mfma_f32_16x16x32_bf16 v[34:37], v[154:157], v[204:207], v[34:37]
	v_mfma_f32_16x16x32_bf16 v[34:37], v[158:161], v[212:215], v[34:37]
	v_mfma_f32_16x16x32_bf16 v[30:33], v[166:169], v[212:215], v[30:33]
	v_mfma_f32_16x16x32_bf16 v[30:33], v[162:165], v[204:207], v[30:33]
	v_mfma_f32_16x16x32_bf16 v[14:17], v[162:165], v[216:219], v[14:17]
	v_mfma_f32_16x16x32_bf16 v[14:17], v[166:169], v[220:223], v[14:17]
	v_mfma_f32_16x16x32_bf16 v[18:21], v[158:161], v[220:223], v[18:21]
	v_mfma_f32_16x16x32_bf16 v[18:21], v[154:157], v[216:219], v[18:21]
	v_mfma_f32_16x16x32_bf16 v[58:61], v[170:173], v[188:191], v[58:61]
	v_mfma_f32_16x16x32_bf16 v[58:61], v[174:177], v[192:195], v[58:61]
	v_mfma_f32_16x16x32_bf16 v[54:57], v[178:181], v[188:191], v[54:57]
	v_mfma_f32_16x16x32_bf16 v[54:57], v[184:187], v[192:195], v[54:57]
	v_mfma_f32_16x16x32_bf16 v[42:45], v[170:173], v[196:199], v[42:45]
	v_mfma_f32_16x16x32_bf16 v[42:45], v[174:177], v[200:203], v[42:45]
	v_mfma_f32_16x16x32_bf16 v[38:41], v[178:181], v[196:199], v[38:41]
	v_mfma_f32_16x16x32_bf16 v[38:41], v[184:187], v[200:203], v[38:41]
	v_mfma_f32_16x16x32_bf16 v[26:29], v[170:173], v[204:207], v[26:29]
	v_mfma_f32_16x16x32_bf16 v[26:29], v[174:177], v[212:215], v[26:29]
	v_mfma_f32_16x16x32_bf16 v[22:25], v[178:181], v[204:207], v[22:25]
	v_mfma_f32_16x16x32_bf16 v[22:25], v[184:187], v[212:215], v[22:25]
	v_mfma_f32_16x16x32_bf16 v[10:13], v[170:173], v[216:219], v[10:13]
	v_mfma_f32_16x16x32_bf16 v[10:13], v[174:177], v[220:223], v[10:13]
	v_mfma_f32_16x16x32_bf16 v[4:7], v[178:181], v[216:219], v[6:9]
	v_mfma_f32_16x16x32_bf16 v[4:7], v[184:187], v[220:223], v[4:7]
	s_barrier
	s_add_i32 s82, 0, 0x18000
	v_add_u32_e32 v3, s82, v183
	s_add_i32 s83, 0, 0x1c000
	ds_read_b128 v[154:157], v3
	ds_read_b128 v[158:161], v3 offset:1024
	ds_read_b128 v[162:165], v3 offset:2048
	ds_read_b128 v[166:169], v3 offset:3072
	v_add_u32_e32 v3, s83, v183
	ds_read_b128 v[170:173], v3
	ds_read_b128 v[174:177], v3 offset:1024
	ds_read_b128 v[178:181], v3 offset:2048
	ds_read_b128 v[184:187], v3 offset:3072
	s_add_u32 s52, s52, 0x100000
	s_addc_u32 s53, s53, 0
	s_mov_b32 m0, s60
	ds_read_b128 v[188:191], v211 offset:32768
	ds_read_b128 v[192:195], v211 offset:33792
	ds_read_b128 v[196:199], v211 offset:34816
	ds_read_b128 v[200:203], v211 offset:35840
	ds_read_b128 v[204:207], v211 offset:36864
	ds_read_b128 v[212:215], v211 offset:37888
	ds_read_b128 v[216:219], v211 offset:38912
	ds_read_b128 v[220:223], v211 offset:39936
	global_load_lds_dwordx4 v134, s[52:53]
	s_mov_b32 m0, s61
	s_nop 0
	global_load_lds_dwordx4 v136, s[52:53]
	s_waitcnt vmcnt(8)
	s_waitcnt lgkmcnt(0)
	s_barrier
	s_waitcnt lgkmcnt(0)
	v_mfma_f32_16x16x32_bf16 v[130:133], v[154:157], v[188:191], v[130:133]
	v_mfma_f32_16x16x32_bf16 v[130:133], v[158:161], v[192:195], v[130:133]
	v_mfma_f32_16x16x32_bf16 v[126:129], v[166:169], v[192:195], v[126:129]
	v_mfma_f32_16x16x32_bf16 v[126:129], v[162:165], v[188:191], v[126:129]
	v_mfma_f32_16x16x32_bf16 v[110:113], v[162:165], v[196:199], v[110:113]
	v_mfma_f32_16x16x32_bf16 v[110:113], v[166:169], v[200:203], v[110:113]
	v_mfma_f32_16x16x32_bf16 v[114:117], v[158:161], v[200:203], v[114:117]
	v_mfma_f32_16x16x32_bf16 v[114:117], v[154:157], v[196:199], v[114:117]
	v_mfma_f32_16x16x32_bf16 v[98:101], v[154:157], v[204:207], v[98:101]
	v_mfma_f32_16x16x32_bf16 v[98:101], v[158:161], v[212:215], v[98:101]
	v_mfma_f32_16x16x32_bf16 v[94:97], v[166:169], v[212:215], v[94:97]
	v_mfma_f32_16x16x32_bf16 v[94:97], v[162:165], v[204:207], v[94:97]
	v_mfma_f32_16x16x32_bf16 v[78:81], v[162:165], v[216:219], v[78:81]
	v_mfma_f32_16x16x32_bf16 v[78:81], v[166:169], v[220:223], v[78:81]
	v_mfma_f32_16x16x32_bf16 v[82:85], v[158:161], v[220:223], v[82:85]
	v_mfma_f32_16x16x32_bf16 v[82:85], v[154:157], v[216:219], v[82:85]
	v_mfma_f32_16x16x32_bf16 v[122:125], v[170:173], v[188:191], v[122:125]
	v_mfma_f32_16x16x32_bf16 v[122:125], v[174:177], v[192:195], v[122:125]
	v_mfma_f32_16x16x32_bf16 v[118:121], v[184:187], v[192:195], v[118:121]
	v_mfma_f32_16x16x32_bf16 v[118:121], v[178:181], v[188:191], v[118:121]
	v_mfma_f32_16x16x32_bf16 v[102:105], v[178:181], v[196:199], v[102:105]
	v_mfma_f32_16x16x32_bf16 v[102:105], v[184:187], v[200:203], v[102:105]
	v_mfma_f32_16x16x32_bf16 v[106:109], v[174:177], v[200:203], v[106:109]
	v_mfma_f32_16x16x32_bf16 v[106:109], v[170:173], v[196:199], v[106:109]
	v_mfma_f32_16x16x32_bf16 v[90:93], v[170:173], v[204:207], v[90:93]
	v_mfma_f32_16x16x32_bf16 v[90:93], v[174:177], v[212:215], v[90:93]
	v_mfma_f32_16x16x32_bf16 v[86:89], v[184:187], v[212:215], v[86:89]
	v_mfma_f32_16x16x32_bf16 v[86:89], v[178:181], v[204:207], v[86:89]
	v_mfma_f32_16x16x32_bf16 v[70:73], v[178:181], v[216:219], v[70:73]
	v_mfma_f32_16x16x32_bf16 v[70:73], v[184:187], v[220:223], v[70:73]
	v_mfma_f32_16x16x32_bf16 v[74:77], v[174:177], v[220:223], v[74:77]
	v_mfma_f32_16x16x32_bf16 v[74:77], v[170:173], v[216:219], v[74:77]
	s_barrier
; #define PG8_STAGE(bufoff, gbase, voff) do { _Pragma("unroll") for (int _i = 0; _i < 2; ++_i) \
;         __builtin_amdgcn_global_load_lds((const unsigned*)((const char*)(gbase) + (voff)[_i]), (PG8_LAS unsigned*)(lds + (bufoff) + ldsw + _i * 8192), 16, 0, 0); } while (0)
; #define PG8_LDA(dst, b, h) do { _Pragma("unroll") for (int m = 0; m < 4; ++m) _Pragma("unroll") for (int k = 0; k < 2; ++k) dst[m][k] = *(const PG8_LAS bf16x8*)(lds + PG8_SA(b, h) + aoff + m * 2048 + k * 1024); } while (0)
; #define PG8_MMA(ai, bj, At, Bt) do { __builtin_amdgcn_s_setprio(1); _Pragma("unroll") for (int m = 0; m < 4; ++m) _Pragma("unroll") for (int n = 0; n < 2; ++n) _Pragma("unroll") for (int k = 0; k < 2; ++k) \
;         acc[ai][bj][m][n] = __builtin_amdgcn_mfma_f32_16x16x32_bf16(Bt[n][k], At[m][k], acc[ai][bj][m][n], 0, 0, 0); __builtin_amdgcn_s_setprio(0); } while (0)
; #define PG8_WAIT_V(n) asm volatile("s_waitcnt vmcnt(" #n ")" ::: "memory")
; #define PG8_WAIT_L(n) asm volatile("s_waitcnt lgkmcnt(" #n ")" ::: "memory")
; #define PG8_BAR __builtin_amdgcn_s_barrier()
; #define PG8_SCHED __builtin_amdgcn_sched_barrier(0)
; template <class Epi, class Sched, bool ALIGN_EPI = false, bool SP2 = false>
; __device__ __forceinline__ void gemm_phase(PG8_LAS unsigned char* lds, const Gemm g, const Sched& S, const Epi& E) {
;     ...
;         for (int t = 0; t < ntc; t += 2) {
;             if constexpr (Epi::MID) { if (ntc == nt && t == (nt >> 1)) E.mid(acc, cur, wr, wc, fr, fq); }
;             const bool last = (t == ntc - 2);
;             const char* a1 = cA + (size_t)(t + 1) * kstep;
;             const char* a2 = last ? nA : cA + (size_t)(t + 2) * kstep; const char* b2 = last ? nB : cB + (size_t)(t + 2) * kstep;
;     ...
;             PG8_LDA(At, 1, 1); PG8_STAGE(PG8_SB(1, 0), b3, voffB); PG8_STAGE(PG8_SB(1, 1), b3 + hstep, voffB); PG8_STAGE(PG8_SA(1, 0), a3, voffA);
;             PG8_WAIT_V(8); PG8_WAIT_L(0); PG8_BAR; PG8_MMA(1, 0, At, B0); PG8_MMA(1, 1, At, B1); PG8_BAR; PG8_SCHED;
	s_add_u32 s100, s52, 0xfff00080
	s_addc_u32 s101, s53, -1
	s_add_u32 s98, s50, 0x80
	s_addc_u32 s99, s51, 0
	s_add_i32 s52, s82, s55
	s_mov_b32 m0, s52
	ds_read_b128 v[188:191], v211 offset:49152
	ds_read_b128 v[192:195], v211 offset:50176
	ds_read_b128 v[196:199], v211 offset:51200
	ds_read_b128 v[200:203], v211 offset:52224
	ds_read_b128 v[204:207], v211 offset:53248
	ds_read_b128 v[212:215], v211 offset:54272
	ds_read_b128 v[216:219], v211 offset:55296
	ds_read_b128 v[220:223], v211 offset:56320
	global_load_lds_dwordx4 v134, s[98:99]
	s_add_i32 m0, s52, 0x2000
	s_add_u32 s50, s50, 0x100080
	s_addc_u32 s51, s51, 0
	s_add_i32 s52, s83, s55
	global_load_lds_dwordx4 v136, s[98:99]
	s_mov_b32 m0, s52
	s_nop 0
	global_load_lds_dwordx4 v134, s[50:51]
	s_add_i32 m0, s52, 0x2000
	s_nop 0
	global_load_lds_dwordx4 v136, s[50:51]
	s_mov_b32 m0, s63
	s_nop 0
	global_load_lds_dwordx4 v134, s[100:101]
	s_mov_b32 m0, s64
	s_nop 0
	global_load_lds_dwordx4 v136, s[100:101]
	s_waitcnt vmcnt(8)
	s_waitcnt lgkmcnt(0)
	s_barrier
	s_waitcnt lgkmcnt(0)
	v_mfma_f32_16x16x32_bf16 v[66:69], v[154:157], v[188:191], v[66:69]
	v_mfma_f32_16x16x32_bf16 v[66:69], v[158:161], v[192:195], v[66:69]
	v_mfma_f32_16x16x32_bf16 v[62:65], v[166:169], v[192:195], v[62:65]
	v_mfma_f32_16x16x32_bf16 v[62:65], v[162:165], v[188:191], v[62:65]
	v_mfma_f32_16x16x32_bf16 v[46:49], v[162:165], v[196:199], v[46:49]
	v_mfma_f32_16x16x32_bf16 v[46:49], v[166:169], v[200:203], v[46:49]
	v_mfma_f32_16x16x32_bf16 v[50:53], v[158:161], v[200:203], v[50:53]
	v_mfma_f32_16x16x32_bf16 v[50:53], v[154:157], v[196:199], v[50:53]
	v_mfma_f32_16x16x32_bf16 v[34:37], v[154:157], v[204:207], v[34:37]
	v_mfma_f32_16x16x32_bf16 v[34:37], v[158:161], v[212:215], v[34:37]
	v_mfma_f32_16x16x32_bf16 v[30:33], v[166:169], v[212:215], v[30:33]
	v_mfma_f32_16x16x32_bf16 v[30:33], v[162:165], v[204:207], v[30:33]
	v_mfma_f32_16x16x32_bf16 v[14:17], v[162:165], v[216:219], v[14:17]
	v_mfma_f32_16x16x32_bf16 v[14:17], v[166:169], v[220:223], v[14:17]
	v_mfma_f32_16x16x32_bf16 v[18:21], v[158:161], v[220:223], v[18:21]
	v_mfma_f32_16x16x32_bf16 v[18:21], v[154:157], v[216:219], v[18:21]
	v_mfma_f32_16x16x32_bf16 v[58:61], v[170:173], v[188:191], v[58:61]
	v_mfma_f32_16x16x32_bf16 v[58:61], v[174:177], v[192:195], v[58:61]
	v_mfma_f32_16x16x32_bf16 v[54:57], v[178:181], v[188:191], v[54:57]
	v_mfma_f32_16x16x32_bf16 v[54:57], v[184:187], v[192:195], v[54:57]
	v_mfma_f32_16x16x32_bf16 v[42:45], v[170:173], v[196:199], v[42:45]
	v_mfma_f32_16x16x32_bf16 v[42:45], v[174:177], v[200:203], v[42:45]
	v_mfma_f32_16x16x32_bf16 v[38:41], v[178:181], v[196:199], v[38:41]
	v_mfma_f32_16x16x32_bf16 v[38:41], v[184:187], v[200:203], v[38:41]
	v_mfma_f32_16x16x32_bf16 v[26:29], v[170:173], v[204:207], v[26:29]
	v_mfma_f32_16x16x32_bf16 v[26:29], v[174:177], v[212:215], v[26:29]
	v_mfma_f32_16x16x32_bf16 v[22:25], v[178:181], v[204:207], v[22:25]
	v_mfma_f32_16x16x32_bf16 v[22:25], v[184:187], v[212:215], v[22:25]
	v_mfma_f32_16x16x32_bf16 v[8:11], v[170:173], v[216:219], v[10:13]
	v_mfma_f32_16x16x32_bf16 v[10:13], v[174:177], v[220:223], v[8:11]
	v_mfma_f32_16x16x32_bf16 v[4:7], v[178:181], v[216:219], v[4:7]
	v_mfma_f32_16x16x32_bf16 v[6:9], v[184:187], v[220:223], v[4:7]
	s_barrier
	s_add_u32 s46, s46, 0x100
	s_addc_u32 s47, s47, 0
	s_cmp_ge_i32 s81, s77
	s_cbranch_scc1 .LBB0_2489
	s_mov_b32 s50, s81
	s_branch .LBB0_2485

; #define PG8_STAGE(bufoff, gbase, voff) do { _Pragma("unroll") for (int _i = 0; _i < 2; ++_i) \
;         __builtin_amdgcn_global_load_lds((const unsigned*)((const char*)(gbase) + (voff)[_i]), (PG8_LAS unsigned*)(lds + (bufoff) + ldsw + _i * 8192), 16, 0, 0); } while (0)
; #define PG8_LDA(dst, b, h) do { _Pragma("unroll") for (int m = 0; m < 4; ++m) _Pragma("unroll") for (int k = 0; k < 2; ++k) dst[m][k] = *(const PG8_LAS bf16x8*)(lds + PG8_SA(b, h) + aoff + m * 2048 + k * 1024); } while (0)
; #define PG8_LDB(dst, b, h) do { _Pragma("unroll") for (int n = 0; n < 2; ++n) _Pragma("unroll") for (int k = 0; k < 2; ++k) dst[n][k] = *(const PG8_LAS bf16x8*)(lds + PG8_SB(b, h) + boff + n * 2048 + k * 1024); } while (0)
; #define PG8_MMA(ai, bj, At, Bt) do { __builtin_amdgcn_s_setprio(1); _Pragma("unroll") for (int m = 0; m < 4; ++m) _Pragma("unroll") for (int n = 0; n < 2; ++n) _Pragma("unroll") for (int k = 0; k < 2; ++k) \
;         acc[ai][bj][m][n] = __builtin_amdgcn_mfma_f32_16x16x32_bf16(Bt[n][k], At[m][k], acc[ai][bj][m][n], 0, 0, 0); __builtin_amdgcn_s_setprio(0); } while (0)
; #define PG8_WAIT_V(n) asm volatile("s_waitcnt vmcnt(" #n ")" ::: "memory")
; #define PG8_WAIT_L(n) asm volatile("s_waitcnt lgkmcnt(" #n ")" ::: "memory")
; #define PG8_BAR __builtin_amdgcn_s_barrier()
; #define PG8_SCHED __builtin_amdgcn_sched_barrier(0)
; template <class Epi, class Sched, bool ALIGN_EPI = false, bool SP2 = false>
; __device__ __forceinline__ void gemm_phase(PG8_LAS unsigned char* lds, const Gemm g, const Sched& S, const Epi& E) {
;     ...
;             if constexpr (SP2) {
;             PG8_LDB(B0, 0, 0); PG8_LDB(B1, 0, 1); PG8_SCHED; PG8_LDA(At, 0, 0); PG8_STAGE(PG8_SA(1, 1), a1 + hstep, voffA);
;             PG8_WAIT_V(8); PG8_WAIT_L(0); PG8_BAR; PG8_MMA(0, 0, At, B0); PG8_MMA(0, 1, At, B1); PG8_BAR; PG8_SCHED;
;             PG8_LDA(At, 0, 1); PG8_STAGE(PG8_SB(0, 0), b2, voffB); PG8_STAGE(PG8_SB(0, 1), b2 + hstep, voffB); PG8_STAGE(PG8_SA(0, 0), a2, voffA);
;             PG8_WAIT_V(8); PG8_WAIT_L(0); PG8_BAR; PG8_MMA(1, 0, At, B0); PG8_MMA(1, 1, At, B1); PG8_BAR; PG8_SCHED;
;             PG8_LDB(B0, 1, 0); PG8_LDB(B1, 1, 1); PG8_SCHED; PG8_LDA(At, 1, 0); PG8_STAGE(PG8_SA(0, 1), a2 + hstep, voffA);
;             PG8_WAIT_V(8); PG8_WAIT_L(0); PG8_BAR; PG8_MMA(0, 0, At, B0); PG8_MMA(0, 1, At, B1); PG8_BAR; PG8_SCHED;
.LBB0_2650:
	ds_read_b128 v[10:13], v195
	ds_read_b128 v[14:17], v195 offset:1024
	ds_read_b128 v[42:45], v195 offset:2048
	ds_read_b128 v[46:49], v195 offset:3072
	ds_read_b128 v[50:53], v238
	ds_read_b128 v[54:57], v238 offset:1024
	ds_read_b128 v[58:61], v238 offset:2048
	ds_read_b128 v[62:65], v238 offset:3072
	s_add_u32 s88, s86, 0xfff00080
	s_addc_u32 s89, s87, -1
	s_cmp_eq_u32 s93, 60
	s_cselect_b32 s91, s19, s89
	s_cselect_b32 s90, s69, s88
	s_cselect_b32 s89, s77, s92
	s_cselect_b32 s88, s79, s85
	s_add_i32 m0, s62, 0xc000
	ds_read_b128 v[66:69], v239
	ds_read_b128 v[70:73], v239 offset:1024
	ds_read_b128 v[170:173], v239 offset:2048
	ds_read_b128 v[174:177], v239 offset:3072
	ds_read_b128 v[178:181], v239 offset:4096
	ds_read_b128 v[208:211], v239 offset:5120
	ds_read_b128 v[212:215], v239 offset:6144
	ds_read_b128 v[216:219], v239 offset:7168
	global_load_lds_dwordx4 v200, s[86:87]
	s_add_i32 m0, s62, 0xe000
	s_nop 0
	global_load_lds_dwordx4 v202, s[86:87]
	s_waitcnt vmcnt(8)
	s_waitcnt lgkmcnt(0)
	s_barrier
	s_waitcnt lgkmcnt(0)
	v_mfma_f32_16x16x32_bf16 v[6:9], v[10:13], v[66:69], v[6:9]
	v_mfma_f32_16x16x32_bf16 v[6:9], v[14:17], v[70:73], v[6:9]
	v_mfma_f32_16x16x32_bf16 v[2:5], v[46:49], v[70:73], v[2:5]
	v_mfma_f32_16x16x32_bf16 v[2:5], v[42:45], v[66:69], v[2:5]
	v_mfma_f32_16x16x32_bf16 v[154:157], v[42:45], v[170:173], v[154:157]
	v_mfma_f32_16x16x32_bf16 v[154:157], v[46:49], v[174:177], v[154:157]
	v_mfma_f32_16x16x32_bf16 v[158:161], v[14:17], v[174:177], v[158:161]
	v_mfma_f32_16x16x32_bf16 v[158:161], v[10:13], v[170:173], v[158:161]
	v_mfma_f32_16x16x32_bf16 v[142:145], v[10:13], v[178:181], v[142:145]
	v_mfma_f32_16x16x32_bf16 v[142:145], v[14:17], v[208:211], v[142:145]
	v_mfma_f32_16x16x32_bf16 v[138:141], v[46:49], v[208:211], v[138:141]
	v_mfma_f32_16x16x32_bf16 v[138:141], v[42:45], v[178:181], v[138:141]
	v_mfma_f32_16x16x32_bf16 v[122:125], v[42:45], v[212:215], v[122:125]
	v_mfma_f32_16x16x32_bf16 v[122:125], v[46:49], v[216:219], v[122:125]
	v_mfma_f32_16x16x32_bf16 v[126:129], v[14:17], v[216:219], v[126:129]
	v_mfma_f32_16x16x32_bf16 v[126:129], v[10:13], v[212:215], v[126:129]
	v_mfma_f32_16x16x32_bf16 v[166:169], v[50:53], v[66:69], v[166:169]
	v_mfma_f32_16x16x32_bf16 v[166:169], v[54:57], v[70:73], v[166:169]
	v_mfma_f32_16x16x32_bf16 v[66:69], v[58:61], v[66:69], v[162:165]
	v_mfma_f32_16x16x32_bf16 v[66:69], v[62:65], v[70:73], v[66:69]
	v_mfma_f32_16x16x32_bf16 v[146:149], v[58:61], v[170:173], v[146:149]
	v_mfma_f32_16x16x32_bf16 v[146:149], v[62:65], v[174:177], v[146:149]
	v_mfma_f32_16x16x32_bf16 v[134:137], v[50:53], v[178:181], v[134:137]
	v_mfma_f32_16x16x32_bf16 v[134:137], v[54:57], v[208:211], v[134:137]
	v_mfma_f32_16x16x32_bf16 v[130:133], v[58:61], v[178:181], v[130:133]
	v_mfma_f32_16x16x32_bf16 v[130:133], v[62:65], v[208:211], v[130:133]
	v_mfma_f32_16x16x32_bf16 v[118:121], v[50:53], v[212:215], v[118:121]
	v_mfma_f32_16x16x32_bf16 v[118:121], v[54:57], v[216:219], v[118:121]
	v_mfma_f32_16x16x32_bf16 v[114:117], v[58:61], v[212:215], v[114:117]
	v_mfma_f32_16x16x32_bf16 v[114:117], v[62:65], v[216:219], v[114:117]
	v_mfma_f32_16x16x32_bf16 v[70:73], v[50:53], v[170:173], v[150:153]
	v_mfma_f32_16x16x32_bf16 v[70:73], v[54:57], v[174:177], v[70:73]
	s_barrier
	s_add_i32 vcc_lo, s96, s61
	s_mov_b32 m0, vcc_lo
	ds_read_b128 v[150:153], v239 offset:16384
	ds_read_b128 v[162:165], v239 offset:17408
	ds_read_b128 v[170:173], v239 offset:18432
	ds_read_b128 v[174:177], v239 offset:19456
	ds_read_b128 v[178:181], v239 offset:20480
	ds_read_b128 v[208:211], v239 offset:21504
	ds_read_b128 v[212:215], v239 offset:22528
	ds_read_b128 v[216:219], v239 offset:23552
	global_load_lds_dwordx4 v186, s[88:89]
	s_add_i32 m0, vcc_lo, 0x2000
	s_add_u32 vcc_lo, s88, 0x100000
	s_addc_u32 vcc_hi, s89, 0
	s_add_i32 s58, s70, s61
	global_load_lds_dwordx4 v190, s[88:89]
	s_mov_b32 m0, s58
	s_nop 0
	global_load_lds_dwordx4 v186, vcc
	s_add_i32 m0, s58, 0x2000
	s_nop 0
	global_load_lds_dwordx4 v190, vcc
	s_mov_b32 m0, s62
	s_nop 0
	global_load_lds_dwordx4 v184, s[90:91]
	s_mov_b32 m0, s63
	s_nop 0
	global_load_lds_dwordx4 v188, s[90:91]
	s_waitcnt vmcnt(8)
	s_waitcnt lgkmcnt(0)
	s_barrier
	s_waitcnt lgkmcnt(0)
	v_mfma_f32_16x16x32_bf16 v[110:113], v[10:13], v[150:153], v[110:113]
	v_mfma_f32_16x16x32_bf16 v[110:113], v[14:17], v[162:165], v[110:113]
	v_mfma_f32_16x16x32_bf16 v[106:109], v[42:45], v[150:153], v[106:109]
	v_mfma_f32_16x16x32_bf16 v[106:109], v[46:49], v[162:165], v[106:109]
	v_mfma_f32_16x16x32_bf16 v[94:97], v[10:13], v[170:173], v[94:97]
	v_mfma_f32_16x16x32_bf16 v[94:97], v[14:17], v[174:177], v[94:97]
	v_mfma_f32_16x16x32_bf16 v[90:93], v[42:45], v[170:173], v[90:93]
	v_mfma_f32_16x16x32_bf16 v[90:93], v[46:49], v[174:177], v[90:93]
	v_mfma_f32_16x16x32_bf16 v[78:81], v[10:13], v[178:181], v[78:81]
	v_mfma_f32_16x16x32_bf16 v[78:81], v[14:17], v[208:211], v[78:81]
	v_mfma_f32_16x16x32_bf16 v[74:77], v[42:45], v[178:181], v[74:77]
	v_mfma_f32_16x16x32_bf16 v[74:77], v[46:49], v[208:211], v[74:77]
	v_mfma_f32_16x16x32_bf16 v[10:13], v[10:13], v[212:215], v[30:33]
	v_mfma_f32_16x16x32_bf16 v[10:13], v[14:17], v[216:219], v[10:13]
	v_mfma_f32_16x16x32_bf16 v[14:17], v[42:45], v[212:215], v[26:29]
	v_mfma_f32_16x16x32_bf16 v[14:17], v[46:49], v[216:219], v[14:17]
	v_mfma_f32_16x16x32_bf16 v[26:29], v[50:53], v[150:153], v[102:105]
	v_mfma_f32_16x16x32_bf16 v[42:45], v[54:57], v[162:165], v[26:29]
	v_mfma_f32_16x16x32_bf16 v[26:29], v[58:61], v[150:153], v[98:101]
	v_mfma_f32_16x16x32_bf16 v[46:49], v[62:65], v[162:165], v[26:29]
	v_mfma_f32_16x16x32_bf16 v[26:29], v[50:53], v[170:173], v[86:89]
	v_mfma_f32_16x16x32_bf16 v[86:89], v[54:57], v[174:177], v[26:29]
	v_mfma_f32_16x16x32_bf16 v[26:29], v[58:61], v[170:173], v[82:85]
	v_mfma_f32_16x16x32_bf16 v[82:85], v[62:65], v[174:177], v[26:29]
	v_mfma_f32_16x16x32_bf16 v[26:29], v[50:53], v[178:181], v[38:41]
	v_mfma_f32_16x16x32_bf16 v[38:41], v[54:57], v[208:211], v[26:29]
	v_mfma_f32_16x16x32_bf16 v[26:29], v[58:61], v[178:181], v[34:37]
	v_mfma_f32_16x16x32_bf16 v[34:37], v[62:65], v[208:211], v[26:29]
	v_mfma_f32_16x16x32_bf16 v[22:25], v[50:53], v[212:215], v[22:25]
	v_mfma_f32_16x16x32_bf16 v[22:25], v[54:57], v[216:219], v[22:25]
	v_mfma_f32_16x16x32_bf16 v[18:21], v[58:61], v[212:215], v[18:21]
	v_mfma_f32_16x16x32_bf16 v[18:21], v[62:65], v[216:219], v[18:21]
	s_barrier
; #define PG8_STAGE(bufoff, gbase, voff) do { _Pragma("unroll") for (int _i = 0; _i < 2; ++_i) \
;         __builtin_amdgcn_global_load_lds((const unsigned*)((const char*)(gbase) + (voff)[_i]), (PG8_LAS unsigned*)(lds + (bufoff) + ldsw + _i * 8192), 16, 0, 0); } while (0)
; #define PG8_LDA(dst, b, h) do { _Pragma("unroll") for (int m = 0; m < 4; ++m) _Pragma("unroll") for (int k = 0; k < 2; ++k) dst[m][k] = *(const PG8_LAS bf16x8*)(lds + PG8_SA(b, h) + aoff + m * 2048 + k * 1024); } while (0)
; #define PG8_LDB(dst, b, h) do { _Pragma("unroll") for (int n = 0; n < 2; ++n) _Pragma("unroll") for (int k = 0; k < 2; ++k) dst[n][k] = *(const PG8_LAS bf16x8*)(lds + PG8_SB(b, h) + boff + n * 2048 + k * 1024); } while (0)
; #define PG8_MMA(ai, bj, At, Bt) do { __builtin_amdgcn_s_setprio(1); _Pragma("unroll") for (int m = 0; m < 4; ++m) _Pragma("unroll") for (int n = 0; n < 2; ++n) _Pragma("unroll") for (int k = 0; k < 2; ++k) \
;         acc[ai][bj][m][n] = __builtin_amdgcn_mfma_f32_16x16x32_bf16(Bt[n][k], At[m][k], acc[ai][bj][m][n], 0, 0, 0); __builtin_amdgcn_s_setprio(0); } while (0)
; #define PG8_WAIT_V(n) asm volatile("s_waitcnt vmcnt(" #n ")" ::: "memory")
; template <class Epi, class Sched, bool ALIGN_EPI = false, bool SP2 = false>
; __device__ __forceinline__ void gemm_phase(PG8_LAS unsigned char* lds, const Gemm g, const Sched& S, const Epi& E) {
;     ...
;         for (int t = 0; t < ntc; t += 2) {
;             if constexpr (Epi::MID) { if (ntc == nt && t == (nt >> 1)) E.mid(acc, cur, wr, wc, fr, fq); }
;             const bool last = (t == ntc - 2);
;             const char* a1 = cA + (size_t)(t + 1) * kstep;
;             const char* a2 = last ? nA : cA + (size_t)(t + 2) * kstep; const char* b2 = last ? nB : cB + (size_t)(t + 2) * kstep;
;             const char* a3 = a2 + kstep; const char* b3 = b2 + kstep;
;             if (last && has_next) S.a_ready(nxt);
;     ...
;             PG8_LDB(B0, 1, 0); PG8_LDB(B1, 1, 1); PG8_SCHED; PG8_LDA(At, 1, 0); PG8_STAGE(PG8_SA(0, 1), a2 + hstep, voffA);
;             PG8_WAIT_V(8); PG8_WAIT_L(0); PG8_BAR; PG8_MMA(0, 0, At, B0); PG8_MMA(0, 1, At, B1); PG8_BAR; PG8_SCHED;
;             PG8_LDA(At, 1, 1); PG8_STAGE(PG8_SB(1, 0), b3, voffB); PG8_STAGE(PG8_SB(1, 1), b3 + hstep, voffB); PG8_STAGE(PG8_SA(1, 0), a3, voffA);
;             PG8_WAIT_V(8); PG8_WAIT_L(0); PG8_BAR; PG8_MMA(1, 0, At, B0); PG8_MMA(1, 1, At, B1); PG8_BAR; PG8_SCHED;
	s_add_i32 s58, 0, 0x18000
	s_add_i32 s59, 0, 0x1c000
	v_add_u32_e32 v54, s58, v1
	v_add_u32_e32 v98, s59, v1
	ds_read_b128 v[26:29], v54
	ds_read_b128 v[30:33], v54 offset:1024
	ds_read_b128 v[50:53], v54 offset:2048
	ds_read_b128 v[54:57], v54 offset:3072
	ds_read_b128 v[58:61], v98
	ds_read_b128 v[62:65], v98 offset:1024
	ds_read_b128 v[170:173], v98 offset:2048
	ds_read_b128 v[174:177], v98 offset:3072
	s_add_u32 s90, s90, 0x100000
	s_addc_u32 s91, s91, 0
	s_mov_b32 m0, s73
	ds_read_b128 v[98:101], v239 offset:32768
	ds_read_b128 v[102:105], v239 offset:33792
	ds_read_b128 v[178:181], v239 offset:34816
	ds_read_b128 v[208:211], v239 offset:35840
	ds_read_b128 v[212:215], v239 offset:36864
	ds_read_b128 v[216:219], v239 offset:37888
	ds_read_b128 v[220:223], v239 offset:38912
	ds_read_b128 v[224:227], v239 offset:39936
	global_load_lds_dwordx4 v184, s[90:91]
	s_mov_b32 m0, s75
	s_nop 0
	global_load_lds_dwordx4 v188, s[90:91]
	s_waitcnt vmcnt(8)
	s_waitcnt lgkmcnt(0)
	s_barrier
	s_waitcnt lgkmcnt(0)
	v_mfma_f32_16x16x32_bf16 v[150:153], v[26:29], v[178:181], v[158:161]
	v_mfma_f32_16x16x32_bf16 v[158:161], v[30:33], v[208:211], v[150:153]
	v_mfma_f32_16x16x32_bf16 v[6:9], v[26:29], v[98:101], v[6:9]
	v_mfma_f32_16x16x32_bf16 v[6:9], v[30:33], v[102:105], v[6:9]
	v_mfma_f32_16x16x32_bf16 v[2:5], v[50:53], v[98:101], v[2:5]
	v_mfma_f32_16x16x32_bf16 v[2:5], v[54:57], v[102:105], v[2:5]
	v_mfma_f32_16x16x32_bf16 v[150:153], v[50:53], v[178:181], v[154:157]
	v_mfma_f32_16x16x32_bf16 v[154:157], v[54:57], v[208:211], v[150:153]
	v_mfma_f32_16x16x32_bf16 v[142:145], v[26:29], v[212:215], v[142:145]
	v_mfma_f32_16x16x32_bf16 v[142:145], v[30:33], v[216:219], v[142:145]
	v_mfma_f32_16x16x32_bf16 v[138:141], v[50:53], v[212:215], v[138:141]
	v_mfma_f32_16x16x32_bf16 v[138:141], v[54:57], v[216:219], v[138:141]
	v_mfma_f32_16x16x32_bf16 v[126:129], v[26:29], v[220:223], v[126:129]
	v_mfma_f32_16x16x32_bf16 v[126:129], v[30:33], v[224:227], v[126:129]
	v_mfma_f32_16x16x32_bf16 v[122:125], v[50:53], v[220:223], v[122:125]
	v_mfma_f32_16x16x32_bf16 v[122:125], v[54:57], v[224:227], v[122:125]
	v_mfma_f32_16x16x32_bf16 v[66:69], v[170:173], v[98:101], v[66:69]
	v_mfma_f32_16x16x32_bf16 v[162:165], v[174:177], v[102:105], v[66:69]
	v_mfma_f32_16x16x32_bf16 v[150:153], v[58:61], v[98:101], v[166:169]
	v_mfma_f32_16x16x32_bf16 v[166:169], v[62:65], v[102:105], v[150:153]
	v_mfma_f32_16x16x32_bf16 v[66:69], v[58:61], v[178:181], v[70:73]
	v_mfma_f32_16x16x32_bf16 v[150:153], v[62:65], v[208:211], v[66:69]
	v_mfma_f32_16x16x32_bf16 v[66:69], v[170:173], v[178:181], v[146:149]
	v_mfma_f32_16x16x32_bf16 v[146:149], v[174:177], v[208:211], v[66:69]
	v_mfma_f32_16x16x32_bf16 v[66:69], v[58:61], v[212:215], v[134:137]
	v_mfma_f32_16x16x32_bf16 v[134:137], v[62:65], v[216:219], v[66:69]
	v_mfma_f32_16x16x32_bf16 v[66:69], v[170:173], v[212:215], v[130:133]
	v_mfma_f32_16x16x32_bf16 v[130:133], v[174:177], v[216:219], v[66:69]
	v_mfma_f32_16x16x32_bf16 v[66:69], v[58:61], v[220:223], v[118:121]
	v_mfma_f32_16x16x32_bf16 v[118:121], v[62:65], v[224:227], v[66:69]
	v_mfma_f32_16x16x32_bf16 v[66:69], v[170:173], v[220:223], v[114:117]
	v_mfma_f32_16x16x32_bf16 v[114:117], v[174:177], v[224:227], v[66:69]
	s_barrier
	s_add_i32 s58, s58, s61
	s_add_u32 s100, s88, 0x80
	s_addc_u32 s101, s89, 0
	s_mov_b32 m0, s58
	s_nop 1
	ds_read_b128 v[66:69], v239 offset:49152
	ds_read_b128 v[70:73], v239 offset:50176
	ds_read_b128 v[178:181], v239 offset:51200
	ds_read_b128 v[208:211], v239 offset:52224
	ds_read_b128 v[212:215], v239 offset:53248
	ds_read_b128 v[216:219], v239 offset:54272
	ds_read_b128 v[220:223], v239 offset:55296
	ds_read_b128 v[224:227], v239 offset:56320
	global_load_lds_dwordx4 v186, s[100:101]
	s_add_i32 m0, s58, 0x2000
	s_add_i32 s58, s59, s61
	global_load_lds_dwordx4 v190, s[100:101]
	s_add_u32 s88, s88, 0x100080
	s_addc_u32 s89, s89, 0
	s_add_u32 s100, s90, 0xfff00080
	s_addc_u32 s101, s91, -1
	s_mov_b32 m0, s58
	s_nop 0
	global_load_lds_dwordx4 v186, s[88:89]
	s_add_i32 m0, s58, 0x2000
	s_nop 0
	global_load_lds_dwordx4 v190, s[88:89]
	s_mov_b32 m0, s29
	s_nop 0
	global_load_lds_dwordx4 v184, s[100:101]
	s_mov_b32 m0, s95
	s_nop 0
	global_load_lds_dwordx4 v188, s[100:101]
	s_waitcnt vmcnt(8)
	s_waitcnt lgkmcnt(0)
	s_barrier
	s_waitcnt lgkmcnt(0)
	v_mfma_f32_16x16x32_bf16 v[98:101], v[26:29], v[66:69], v[110:113]
	v_mfma_f32_16x16x32_bf16 v[110:113], v[30:33], v[70:73], v[98:101]
	v_mfma_f32_16x16x32_bf16 v[94:97], v[26:29], v[178:181], v[94:97]
	v_mfma_f32_16x16x32_bf16 v[94:97], v[30:33], v[208:211], v[94:97]
	v_mfma_f32_16x16x32_bf16 v[78:81], v[26:29], v[212:215], v[78:81]
	v_mfma_f32_16x16x32_bf16 v[78:81], v[30:33], v[216:219], v[78:81]
	v_mfma_f32_16x16x32_bf16 v[10:13], v[26:29], v[220:223], v[10:13]
	v_mfma_f32_16x16x32_bf16 v[30:33], v[30:33], v[224:227], v[10:13]
	v_mfma_f32_16x16x32_bf16 v[98:101], v[50:53], v[66:69], v[106:109]
	v_mfma_f32_16x16x32_bf16 v[106:109], v[54:57], v[70:73], v[98:101]
	v_mfma_f32_16x16x32_bf16 v[90:93], v[50:53], v[178:181], v[90:93]
	v_mfma_f32_16x16x32_bf16 v[90:93], v[54:57], v[208:211], v[90:93]
	v_mfma_f32_16x16x32_bf16 v[74:77], v[50:53], v[212:215], v[74:77]
	v_mfma_f32_16x16x32_bf16 v[74:77], v[54:57], v[216:219], v[74:77]
	v_mfma_f32_16x16x32_bf16 v[10:13], v[50:53], v[220:223], v[14:17]
	v_mfma_f32_16x16x32_bf16 v[26:29], v[54:57], v[224:227], v[10:13]
	v_mfma_f32_16x16x32_bf16 v[10:13], v[58:61], v[66:69], v[42:45]
	v_mfma_f32_16x16x32_bf16 v[102:105], v[62:65], v[70:73], v[10:13]
	v_mfma_f32_16x16x32_bf16 v[10:13], v[170:173], v[66:69], v[46:49]
	v_mfma_f32_16x16x32_bf16 v[98:101], v[174:177], v[70:73], v[10:13]
	v_mfma_f32_16x16x32_bf16 v[10:13], v[58:61], v[178:181], v[86:89]
	v_mfma_f32_16x16x32_bf16 v[86:89], v[62:65], v[208:211], v[10:13]
	v_mfma_f32_16x16x32_bf16 v[10:13], v[170:173], v[178:181], v[82:85]
	v_mfma_f32_16x16x32_bf16 v[82:85], v[174:177], v[208:211], v[10:13]
	v_mfma_f32_16x16x32_bf16 v[10:13], v[58:61], v[212:215], v[38:41]
	v_mfma_f32_16x16x32_bf16 v[38:41], v[62:65], v[216:219], v[10:13]
	v_mfma_f32_16x16x32_bf16 v[10:13], v[170:173], v[212:215], v[34:37]
	v_mfma_f32_16x16x32_bf16 v[34:37], v[174:177], v[216:219], v[10:13]
	v_mfma_f32_16x16x32_bf16 v[10:13], v[58:61], v[220:223], v[22:25]
	v_mfma_f32_16x16x32_bf16 v[22:25], v[62:65], v[224:227], v[10:13]
	v_mfma_f32_16x16x32_bf16 v[10:13], v[170:173], v[220:223], v[18:21]
	v_mfma_f32_16x16x32_bf16 v[18:21], v[174:177], v[224:227], v[10:13]
	s_barrier
	s_add_i32 s93, s93, 2
	s_add_u32 s86, s86, 0x100
	s_addc_u32 s87, s87, 0
	s_add_u32 s85, s85, 0x100
	s_addc_u32 s92, s92, 0
	s_cmp_gt_u32 s93, 61
	s_cbranch_scc0 .LBB0_2650
	s_and_b64 vcc, exec, s[42:43]
	s_cbranch_vccz .LBB0_2653
	s_barrier

; #define PG8_STAGE(bufoff, gbase, voff) do { _Pragma("unroll") for (int _i = 0; _i < 2; ++_i) \
;         __builtin_amdgcn_global_load_lds((const unsigned*)((const char*)(gbase) + (voff)[_i]), (PG8_LAS unsigned*)(lds + (bufoff) + ldsw + _i * 8192), 16, 0, 0); } while (0)
; #define PG8_LDA(dst, b, h) do { _Pragma("unroll") for (int m = 0; m < 4; ++m) _Pragma("unroll") for (int k = 0; k < 2; ++k) dst[m][k] = *(const PG8_LAS bf16x8*)(lds + PG8_SA(b, h) + aoff + m * 2048 + k * 1024); } while (0)
; #define PG8_LDB(dst, b, h) do { _Pragma("unroll") for (int n = 0; n < 2; ++n) _Pragma("unroll") for (int k = 0; k < 2; ++k) dst[n][k] = *(const PG8_LAS bf16x8*)(lds + PG8_SB(b, h) + boff + n * 2048 + k * 1024); } while (0)
; #define PG8_MMA(ai, bj, At, Bt) do { __builtin_amdgcn_s_setprio(1); _Pragma("unroll") for (int m = 0; m < 4; ++m) _Pragma("unroll") for (int n = 0; n < 2; ++n) _Pragma("unroll") for (int k = 0; k < 2; ++k) \
;         acc[ai][bj][m][n] = __builtin_amdgcn_mfma_f32_16x16x32_bf16(Bt[n][k], At[m][k], acc[ai][bj][m][n], 0, 0, 0); __builtin_amdgcn_s_setprio(0); } while (0)
; #define PG8_WAIT_V(n) asm volatile("s_waitcnt vmcnt(" #n ")" ::: "memory")
; #define PG8_WAIT_L(n) asm volatile("s_waitcnt lgkmcnt(" #n ")" ::: "memory")
; #define PG8_BAR __builtin_amdgcn_s_barrier()
; #define PG8_SCHED __builtin_amdgcn_sched_barrier(0)
; template <class Epi, class Sched, bool ALIGN_EPI = false, bool SP2 = false>
; __device__ __forceinline__ void gemm_phase(PG8_LAS unsigned char* lds, const Gemm g, const Sched& S, const Epi& E) {
;     ...
;             if constexpr (SP2) {
;             PG8_LDB(B0, 0, 0); PG8_LDB(B1, 0, 1); PG8_SCHED; PG8_LDA(At, 0, 0); PG8_STAGE(PG8_SA(1, 1), a1 + hstep, voffA);
;             PG8_WAIT_V(8); PG8_WAIT_L(0); PG8_BAR; PG8_MMA(0, 0, At, B0); PG8_MMA(0, 1, At, B1); PG8_BAR; PG8_SCHED;
;             PG8_LDA(At, 0, 1); PG8_STAGE(PG8_SB(0, 0), b2, voffB); PG8_STAGE(PG8_SB(0, 1), b2 + hstep, voffB); PG8_STAGE(PG8_SA(0, 0), a2, voffA);
;             PG8_WAIT_V(8); PG8_WAIT_L(0); PG8_BAR; PG8_MMA(1, 0, At, B0); PG8_MMA(1, 1, At, B1); PG8_BAR; PG8_SCHED;
.LBB0_3522:
	ds_read_b128 v[144:147], v177
	ds_read_b128 v[148:151], v177 offset:1024
	ds_read_b128 v[152:155], v177 offset:2048
	ds_read_b128 v[156:159], v177 offset:3072
	ds_read_b128 v[160:163], v178
	ds_read_b128 v[164:167], v178 offset:1024
	ds_read_b128 v[168:171], v178 offset:2048
	ds_read_b128 v[172:175], v178 offset:3072
	s_add_u32 s40, s38, 0x100
	s_addc_u32 s41, s39, 0
	s_cmp_eq_u32 s69, s71
	s_cselect_b32 s45, s35, s41
	s_cselect_b32 s44, s34, s40
	s_cselect_b32 s43, s37, s70
	s_cselect_b32 s42, s36, s31
	s_add_i32 m0, s51, 0xc000
	ds_read_b128 v[180:183], v179
	ds_read_b128 v[184:187], v179 offset:1024
	ds_read_b128 v[188:191], v179 offset:2048
	ds_read_b128 v[192:195], v179 offset:3072
	ds_read_b128 v[196:199], v179 offset:4096
	ds_read_b128 v[200:203], v179 offset:5120
	ds_read_b128 v[204:207], v179 offset:6144
	ds_read_b128 v[208:211], v179 offset:7168
	global_load_lds_dwordx4 v138, s[38:39]
	s_add_i32 m0, s51, 0xe000
	s_nop 0
	global_load_lds_dwordx4 v140, s[38:39]
	s_waitcnt vmcnt(8)
	s_waitcnt lgkmcnt(0)
	s_barrier
	s_waitcnt lgkmcnt(0)
	v_mfma_f32_16x16x32_bf16 v[126:129], v[144:147], v[180:183], v[126:129]
	v_mfma_f32_16x16x32_bf16 v[126:129], v[148:151], v[184:187], v[126:129]
	v_mfma_f32_16x16x32_bf16 v[122:125], v[156:159], v[184:187], v[122:125]
	v_mfma_f32_16x16x32_bf16 v[122:125], v[152:155], v[180:183], v[122:125]
	v_mfma_f32_16x16x32_bf16 v[106:109], v[152:155], v[188:191], v[106:109]
	v_mfma_f32_16x16x32_bf16 v[106:109], v[156:159], v[192:195], v[106:109]
	v_mfma_f32_16x16x32_bf16 v[110:113], v[148:151], v[192:195], v[110:113]
	v_mfma_f32_16x16x32_bf16 v[110:113], v[144:147], v[188:191], v[110:113]
	v_mfma_f32_16x16x32_bf16 v[94:97], v[144:147], v[196:199], v[94:97]
	v_mfma_f32_16x16x32_bf16 v[94:97], v[148:151], v[200:203], v[94:97]
	v_mfma_f32_16x16x32_bf16 v[90:93], v[156:159], v[200:203], v[90:93]
	v_mfma_f32_16x16x32_bf16 v[90:93], v[152:155], v[196:199], v[90:93]
	v_mfma_f32_16x16x32_bf16 v[74:77], v[152:155], v[204:207], v[74:77]
	v_mfma_f32_16x16x32_bf16 v[74:77], v[156:159], v[208:211], v[74:77]
	v_mfma_f32_16x16x32_bf16 v[78:81], v[148:151], v[208:211], v[78:81]
	v_mfma_f32_16x16x32_bf16 v[78:81], v[144:147], v[204:207], v[78:81]
	v_mfma_f32_16x16x32_bf16 v[118:121], v[160:163], v[180:183], v[118:121]
	v_mfma_f32_16x16x32_bf16 v[118:121], v[164:167], v[184:187], v[118:121]
	v_mfma_f32_16x16x32_bf16 v[114:117], v[172:175], v[184:187], v[114:117]
	v_mfma_f32_16x16x32_bf16 v[114:117], v[168:171], v[180:183], v[114:117]
	v_mfma_f32_16x16x32_bf16 v[98:101], v[168:171], v[188:191], v[98:101]
	v_mfma_f32_16x16x32_bf16 v[98:101], v[172:175], v[192:195], v[98:101]
	v_mfma_f32_16x16x32_bf16 v[102:105], v[164:167], v[192:195], v[102:105]
	v_mfma_f32_16x16x32_bf16 v[102:105], v[160:163], v[188:191], v[102:105]
	v_mfma_f32_16x16x32_bf16 v[86:89], v[160:163], v[196:199], v[86:89]
	v_mfma_f32_16x16x32_bf16 v[86:89], v[164:167], v[200:203], v[86:89]
	v_mfma_f32_16x16x32_bf16 v[82:85], v[172:175], v[200:203], v[82:85]
	v_mfma_f32_16x16x32_bf16 v[82:85], v[168:171], v[196:199], v[82:85]
	v_mfma_f32_16x16x32_bf16 v[66:69], v[168:171], v[204:207], v[66:69]
	v_mfma_f32_16x16x32_bf16 v[66:69], v[172:175], v[208:211], v[66:69]
	v_mfma_f32_16x16x32_bf16 v[70:73], v[164:167], v[208:211], v[70:73]
	v_mfma_f32_16x16x32_bf16 v[70:73], v[160:163], v[204:207], v[70:73]
	s_barrier
	s_add_i32 s38, s63, s50
	s_mov_b32 m0, s38
	ds_read_b128 v[180:183], v179 offset:16384
	ds_read_b128 v[184:187], v179 offset:17408
	ds_read_b128 v[188:191], v179 offset:18432
	ds_read_b128 v[192:195], v179 offset:19456
	ds_read_b128 v[196:199], v179 offset:20480
	ds_read_b128 v[200:203], v179 offset:21504
	ds_read_b128 v[204:207], v179 offset:22528
	ds_read_b128 v[208:211], v179 offset:23552
	global_load_lds_dwordx4 v130, s[42:43]
	s_add_i32 m0, s38, 0x2000
	s_add_u32 s38, s42, 0x300000
	s_addc_u32 s39, s43, 0
	s_add_i32 s58, s64, s50
	global_load_lds_dwordx4 v132, s[42:43]
	s_mov_b32 m0, s58
	s_nop 0
	global_load_lds_dwordx4 v130, s[38:39]
	s_add_i32 m0, s58, 0x2000
	s_nop 0
	global_load_lds_dwordx4 v132, s[38:39]
	s_mov_b32 m0, s51
	s_nop 0
	global_load_lds_dwordx4 v130, s[44:45]
	s_mov_b32 m0, s52
	s_nop 0
	global_load_lds_dwordx4 v132, s[44:45]
	s_waitcnt vmcnt(8)
	s_waitcnt lgkmcnt(0)
	s_barrier
	s_waitcnt lgkmcnt(0)
	v_mfma_f32_16x16x32_bf16 v[62:65], v[144:147], v[180:183], v[62:65]
	v_mfma_f32_16x16x32_bf16 v[62:65], v[148:151], v[184:187], v[62:65]
	v_mfma_f32_16x16x32_bf16 v[58:61], v[156:159], v[184:187], v[58:61]
	v_mfma_f32_16x16x32_bf16 v[58:61], v[152:155], v[180:183], v[58:61]
	v_mfma_f32_16x16x32_bf16 v[42:45], v[152:155], v[188:191], v[42:45]
	v_mfma_f32_16x16x32_bf16 v[42:45], v[156:159], v[192:195], v[42:45]
	v_mfma_f32_16x16x32_bf16 v[46:49], v[148:151], v[192:195], v[46:49]
	v_mfma_f32_16x16x32_bf16 v[46:49], v[144:147], v[188:191], v[46:49]
	v_mfma_f32_16x16x32_bf16 v[30:33], v[144:147], v[196:199], v[30:33]
	v_mfma_f32_16x16x32_bf16 v[30:33], v[148:151], v[200:203], v[30:33]
	v_mfma_f32_16x16x32_bf16 v[26:29], v[156:159], v[200:203], v[26:29]
	v_mfma_f32_16x16x32_bf16 v[26:29], v[152:155], v[196:199], v[26:29]
	v_mfma_f32_16x16x32_bf16 v[10:13], v[152:155], v[204:207], v[10:13]
	v_mfma_f32_16x16x32_bf16 v[10:13], v[156:159], v[208:211], v[10:13]
	v_mfma_f32_16x16x32_bf16 v[14:17], v[148:151], v[208:211], v[14:17]
	v_mfma_f32_16x16x32_bf16 v[14:17], v[144:147], v[204:207], v[14:17]
	v_mfma_f32_16x16x32_bf16 v[54:57], v[160:163], v[180:183], v[54:57]
	v_mfma_f32_16x16x32_bf16 v[54:57], v[164:167], v[184:187], v[54:57]
	v_mfma_f32_16x16x32_bf16 v[50:53], v[172:175], v[184:187], v[50:53]
	v_mfma_f32_16x16x32_bf16 v[50:53], v[168:171], v[180:183], v[50:53]
	v_mfma_f32_16x16x32_bf16 v[34:37], v[168:171], v[188:191], v[34:37]
	v_mfma_f32_16x16x32_bf16 v[34:37], v[172:175], v[192:195], v[34:37]
	v_mfma_f32_16x16x32_bf16 v[38:41], v[164:167], v[192:195], v[38:41]
	v_mfma_f32_16x16x32_bf16 v[38:41], v[160:163], v[188:191], v[38:41]
	v_mfma_f32_16x16x32_bf16 v[22:25], v[160:163], v[196:199], v[22:25]
	v_mfma_f32_16x16x32_bf16 v[22:25], v[164:167], v[200:203], v[22:25]
	v_mfma_f32_16x16x32_bf16 v[18:21], v[172:175], v[200:203], v[18:21]
	v_mfma_f32_16x16x32_bf16 v[18:21], v[168:171], v[196:199], v[18:21]
	v_mfma_f32_16x16x32_bf16 v[2:5], v[168:171], v[204:207], v[2:5]
	v_mfma_f32_16x16x32_bf16 v[2:5], v[172:175], v[208:211], v[2:5]
	v_mfma_f32_16x16x32_bf16 v[6:9], v[164:167], v[208:211], v[6:9]
	v_mfma_f32_16x16x32_bf16 v[6:9], v[160:163], v[204:207], v[6:9]
	s_barrier
; #define PG8_STAGE(bufoff, gbase, voff) do { _Pragma("unroll") for (int _i = 0; _i < 2; ++_i) \
;         __builtin_amdgcn_global_load_lds((const unsigned*)((const char*)(gbase) + (voff)[_i]), (PG8_LAS unsigned*)(lds + (bufoff) + ldsw + _i * 8192), 16, 0, 0); } while (0)
; #define PG8_LDA(dst, b, h) do { _Pragma("unroll") for (int m = 0; m < 4; ++m) _Pragma("unroll") for (int k = 0; k < 2; ++k) dst[m][k] = *(const PG8_LAS bf16x8*)(lds + PG8_SA(b, h) + aoff + m * 2048 + k * 1024); } while (0)
; #define PG8_LDB(dst, b, h) do { _Pragma("unroll") for (int n = 0; n < 2; ++n) _Pragma("unroll") for (int k = 0; k < 2; ++k) dst[n][k] = *(const PG8_LAS bf16x8*)(lds + PG8_SB(b, h) + boff + n * 2048 + k * 1024); } while (0)
; #define PG8_MMA(ai, bj, At, Bt) do { __builtin_amdgcn_s_setprio(1); _Pragma("unroll") for (int m = 0; m < 4; ++m) _Pragma("unroll") for (int n = 0; n < 2; ++n) _Pragma("unroll") for (int k = 0; k < 2; ++k) \
;         acc[ai][bj][m][n] = __builtin_amdgcn_mfma_f32_16x16x32_bf16(Bt[n][k], At[m][k], acc[ai][bj][m][n], 0, 0, 0); __builtin_amdgcn_s_setprio(0); } while (0)
; #define PG8_WAIT_V(n) asm volatile("s_waitcnt vmcnt(" #n ")" ::: "memory")
; #define PG8_WAIT_L(n) asm volatile("s_waitcnt lgkmcnt(" #n ")" ::: "memory")
; #define PG8_BAR __builtin_amdgcn_s_barrier()
; #define PG8_SCHED __builtin_amdgcn_sched_barrier(0)
; template <class Epi, class Sched, bool ALIGN_EPI = false, bool SP2 = false>
; __device__ __forceinline__ void gemm_phase(PG8_LAS unsigned char* lds, const Gemm g, const Sched& S, const Epi& E) {
;     ...
;             PG8_LDB(B0, 1, 0); PG8_LDB(B1, 1, 1); PG8_SCHED; PG8_LDA(At, 1, 0); PG8_STAGE(PG8_SA(0, 1), a2 + hstep, voffA);
;             PG8_WAIT_V(8); PG8_WAIT_L(0); PG8_BAR; PG8_MMA(0, 0, At, B0); PG8_MMA(0, 1, At, B1); PG8_BAR; PG8_SCHED;
;             PG8_LDA(At, 1, 1); PG8_STAGE(PG8_SB(1, 0), b3, voffB); PG8_STAGE(PG8_SB(1, 1), b3 + hstep, voffB); PG8_STAGE(PG8_SA(1, 0), a3, voffA);
;             PG8_WAIT_V(8); PG8_WAIT_L(0); PG8_BAR; PG8_MMA(1, 0, At, B0); PG8_MMA(1, 1, At, B1); PG8_BAR; PG8_SCHED;
;     ...
;         if constexpr (ALIGN_EPI) { if (wr == 0) PG8_BAR; }
;         if constexpr (!Epi::AFTER_DRAIN) { E(acc, cur, wr, wc, fr, fq); S.done(cur); }
;         if (!has_next) break;
	s_add_i32 s58, 0, 0x18000
	v_add_u32_e32 v134, s58, v1
	s_add_i32 s59, 0, 0x1c000
	ds_read_b128 v[144:147], v134
	ds_read_b128 v[148:151], v134 offset:1024
	ds_read_b128 v[152:155], v134 offset:2048
	ds_read_b128 v[156:159], v134 offset:3072
	v_add_u32_e32 v134, s59, v1
	ds_read_b128 v[160:163], v134
	ds_read_b128 v[164:167], v134 offset:1024
	ds_read_b128 v[168:171], v134 offset:2048
	ds_read_b128 v[172:175], v134 offset:3072
	s_add_u32 s38, s44, 0x300000
	s_addc_u32 s39, s45, 0
	s_mov_b32 m0, s53
	ds_read_b128 v[180:183], v179 offset:32768
	ds_read_b128 v[184:187], v179 offset:33792
	ds_read_b128 v[188:191], v179 offset:34816
	ds_read_b128 v[192:195], v179 offset:35840
	ds_read_b128 v[196:199], v179 offset:36864
	ds_read_b128 v[200:203], v179 offset:37888
	ds_read_b128 v[204:207], v179 offset:38912
	ds_read_b128 v[208:211], v179 offset:39936
	global_load_lds_dwordx4 v130, s[38:39]
	s_mov_b32 m0, s54
	s_nop 0
	global_load_lds_dwordx4 v132, s[38:39]
	s_waitcnt vmcnt(8)
	s_waitcnt lgkmcnt(0)
	s_barrier
	s_waitcnt lgkmcnt(0)
	v_mfma_f32_16x16x32_bf16 v[126:129], v[144:147], v[180:183], v[126:129]
	v_mfma_f32_16x16x32_bf16 v[126:129], v[148:151], v[184:187], v[126:129]
	v_mfma_f32_16x16x32_bf16 v[122:125], v[156:159], v[184:187], v[122:125]
	v_mfma_f32_16x16x32_bf16 v[122:125], v[152:155], v[180:183], v[122:125]
	v_mfma_f32_16x16x32_bf16 v[106:109], v[152:155], v[188:191], v[106:109]
	v_mfma_f32_16x16x32_bf16 v[106:109], v[156:159], v[192:195], v[106:109]
	v_mfma_f32_16x16x32_bf16 v[110:113], v[148:151], v[192:195], v[110:113]
	v_mfma_f32_16x16x32_bf16 v[110:113], v[144:147], v[188:191], v[110:113]
	v_mfma_f32_16x16x32_bf16 v[94:97], v[144:147], v[196:199], v[94:97]
	v_mfma_f32_16x16x32_bf16 v[94:97], v[148:151], v[200:203], v[94:97]
	v_mfma_f32_16x16x32_bf16 v[90:93], v[156:159], v[200:203], v[90:93]
	v_mfma_f32_16x16x32_bf16 v[90:93], v[152:155], v[196:199], v[90:93]
	v_mfma_f32_16x16x32_bf16 v[74:77], v[152:155], v[204:207], v[74:77]
	v_mfma_f32_16x16x32_bf16 v[74:77], v[156:159], v[208:211], v[74:77]
	v_mfma_f32_16x16x32_bf16 v[78:81], v[148:151], v[208:211], v[78:81]
	v_mfma_f32_16x16x32_bf16 v[78:81], v[144:147], v[204:207], v[78:81]
	v_mfma_f32_16x16x32_bf16 v[118:121], v[160:163], v[180:183], v[118:121]
	v_mfma_f32_16x16x32_bf16 v[118:121], v[164:167], v[184:187], v[118:121]
	v_mfma_f32_16x16x32_bf16 v[114:117], v[172:175], v[184:187], v[114:117]
	v_mfma_f32_16x16x32_bf16 v[114:117], v[168:171], v[180:183], v[114:117]
	v_mfma_f32_16x16x32_bf16 v[98:101], v[168:171], v[188:191], v[98:101]
	v_mfma_f32_16x16x32_bf16 v[98:101], v[172:175], v[192:195], v[98:101]
	v_mfma_f32_16x16x32_bf16 v[102:105], v[164:167], v[192:195], v[102:105]
	v_mfma_f32_16x16x32_bf16 v[102:105], v[160:163], v[188:191], v[102:105]
	v_mfma_f32_16x16x32_bf16 v[86:89], v[160:163], v[196:199], v[86:89]
	v_mfma_f32_16x16x32_bf16 v[86:89], v[164:167], v[200:203], v[86:89]
	v_mfma_f32_16x16x32_bf16 v[82:85], v[172:175], v[200:203], v[82:85]
	v_mfma_f32_16x16x32_bf16 v[82:85], v[168:171], v[196:199], v[82:85]
	v_mfma_f32_16x16x32_bf16 v[66:69], v[168:171], v[204:207], v[66:69]
	v_mfma_f32_16x16x32_bf16 v[66:69], v[172:175], v[208:211], v[66:69]
	v_mfma_f32_16x16x32_bf16 v[70:73], v[164:167], v[208:211], v[70:73]
	v_mfma_f32_16x16x32_bf16 v[70:73], v[160:163], v[204:207], v[70:73]
	s_barrier
	s_add_i32 s38, s58, s50
	s_add_u32 s98, s42, 0x80
	s_addc_u32 s99, s43, 0
	s_add_u32 s100, s44, 0x80
	s_addc_u32 s101, s45, 0
	s_mov_b32 m0, s38
	ds_read_b128 v[180:183], v179 offset:49152
	ds_read_b128 v[184:187], v179 offset:50176
	ds_read_b128 v[188:191], v179 offset:51200
	ds_read_b128 v[192:195], v179 offset:52224
	ds_read_b128 v[196:199], v179 offset:53248
	ds_read_b128 v[200:203], v179 offset:54272
	ds_read_b128 v[204:207], v179 offset:55296
	ds_read_b128 v[208:211], v179 offset:56320
	global_load_lds_dwordx4 v130, s[98:99]
	s_add_i32 m0, s38, 0x2000
	s_add_u32 s38, s42, 0x300080
	s_addc_u32 s39, s43, 0
	s_add_i32 s42, s59, s50
	global_load_lds_dwordx4 v132, s[98:99]
	s_mov_b32 m0, s42
	s_nop 0
	global_load_lds_dwordx4 v130, s[38:39]
	s_add_i32 m0, s42, 0x2000
	s_nop 0
	global_load_lds_dwordx4 v132, s[38:39]
	s_mov_b32 m0, s57
	s_nop 0
	global_load_lds_dwordx4 v130, s[100:101]
	s_mov_b32 m0, s60
	s_nop 0
	global_load_lds_dwordx4 v132, s[100:101]
	s_waitcnt vmcnt(8)
	s_waitcnt lgkmcnt(0)
	s_barrier
	s_waitcnt lgkmcnt(0)
	v_mfma_f32_16x16x32_bf16 v[62:65], v[144:147], v[180:183], v[62:65]
	v_mfma_f32_16x16x32_bf16 v[62:65], v[148:151], v[184:187], v[62:65]
	v_mfma_f32_16x16x32_bf16 v[58:61], v[156:159], v[184:187], v[58:61]
	v_mfma_f32_16x16x32_bf16 v[58:61], v[152:155], v[180:183], v[58:61]
	v_mfma_f32_16x16x32_bf16 v[42:45], v[152:155], v[188:191], v[42:45]
	v_mfma_f32_16x16x32_bf16 v[42:45], v[156:159], v[192:195], v[42:45]
	v_mfma_f32_16x16x32_bf16 v[46:49], v[148:151], v[192:195], v[46:49]
	v_mfma_f32_16x16x32_bf16 v[46:49], v[144:147], v[188:191], v[46:49]
	v_mfma_f32_16x16x32_bf16 v[30:33], v[144:147], v[196:199], v[30:33]
	v_mfma_f32_16x16x32_bf16 v[30:33], v[148:151], v[200:203], v[30:33]
	v_mfma_f32_16x16x32_bf16 v[26:29], v[156:159], v[200:203], v[26:29]
	v_mfma_f32_16x16x32_bf16 v[26:29], v[152:155], v[196:199], v[26:29]
	v_mfma_f32_16x16x32_bf16 v[10:13], v[152:155], v[204:207], v[10:13]
	v_mfma_f32_16x16x32_bf16 v[10:13], v[156:159], v[208:211], v[10:13]
	v_mfma_f32_16x16x32_bf16 v[14:17], v[148:151], v[208:211], v[14:17]
	v_mfma_f32_16x16x32_bf16 v[14:17], v[144:147], v[204:207], v[14:17]
	v_mfma_f32_16x16x32_bf16 v[54:57], v[160:163], v[180:183], v[54:57]
	v_mfma_f32_16x16x32_bf16 v[54:57], v[164:167], v[184:187], v[54:57]
	v_mfma_f32_16x16x32_bf16 v[50:53], v[172:175], v[184:187], v[50:53]
	v_mfma_f32_16x16x32_bf16 v[50:53], v[168:171], v[180:183], v[50:53]
	v_mfma_f32_16x16x32_bf16 v[34:37], v[168:171], v[188:191], v[34:37]
	v_mfma_f32_16x16x32_bf16 v[34:37], v[172:175], v[192:195], v[34:37]
	v_mfma_f32_16x16x32_bf16 v[38:41], v[164:167], v[192:195], v[38:41]
	v_mfma_f32_16x16x32_bf16 v[38:41], v[160:163], v[188:191], v[38:41]
	v_mfma_f32_16x16x32_bf16 v[22:25], v[160:163], v[196:199], v[22:25]
	v_mfma_f32_16x16x32_bf16 v[22:25], v[164:167], v[200:203], v[22:25]
	v_mfma_f32_16x16x32_bf16 v[18:21], v[172:175], v[200:203], v[18:21]
	v_mfma_f32_16x16x32_bf16 v[18:21], v[168:171], v[196:199], v[18:21]
	v_mfma_f32_16x16x32_bf16 v[2:5], v[168:171], v[204:207], v[2:5]
	v_mfma_f32_16x16x32_bf16 v[2:5], v[172:175], v[208:211], v[2:5]
	v_mfma_f32_16x16x32_bf16 v[6:9], v[164:167], v[208:211], v[6:9]
	v_mfma_f32_16x16x32_bf16 v[6:9], v[160:163], v[204:207], v[6:9]
	s_barrier
	s_add_i32 s42, s71, 2
	s_add_u32 s31, s31, 0x100
	s_addc_u32 s70, s70, 0
	s_cmp_ge_i32 s71, s69
	s_mov_b64 s[38:39], s[40:41]
	s_mov_b32 s71, s42
	s_cbranch_scc0 .LBB0_3522
	s_and_b64 vcc, exec, s[20:21]
	s_cbranch_vccz .LBB0_3543
	s_barrier
	v_lshl_or_b32 v144, s5, 8, v176
	s_cmpk_eq_i32 s69, 0xc0
	s_mov_b64 s[38:39], -1
	s_cbranch_scc0 .LBB0_3544
